# removed redundant pre-loop accumulator zero block from hot path (9 GEMM bodies) + attention K/V staging loads issued up-front (6 iterations prefetched, k_gain loads hoisted)
# speedup vs baseline: 1.0239x; 1.0239x over previous
;     __device__ bool next(int i, Unit& u) const { const int L = i * G + c; if (L >= 512) return false; u.pm = 0; u.pn = L; u.offA = 0; u.offB = (size_t)L * 256 * 256 * 2; return true; }
; template <class Epi, class Sched>
; __device__ __forceinline__ void gemm_phase(LAS unsigned char* lds, const Gemm g, const Sched& S, const Epi& E) {
;     ...
;         const bool has_next = S.next(ui + 1, nxt);
;         const char* nA = has_next ? (const char*)g.A + nxt.offA : cA; const char* nB = has_next ? (const char*)g.Bt + nxt.offB : cB;
;         for (int t = 0; t < nt; t += 2) {
;             const bool last = (t == nt - 2);
;             const char* a1 = cA + (size_t)(t + 1) * kstep;
;             const char* a2 = last ? nA : cA + (size_t)(t + 2) * kstep; const char* b2 = last ? nB : cB + (size_t)(t + 2) * kstep;
;     ...
; #pragma unroll
;         for (int a = 0; a < 2; ++a)
; #pragma unroll
;             for (int b = 0; b < 2; ++b)
; #pragma unroll
;                 for (int m = 0; m < 4; ++m)
; #pragma unroll
;                     for (int n = 0; n < 2; ++n) acc[a][b][m][n] = (f32x4){0.f, 0.f, 0.f, 0.f};
;         cur = nxt; cA = nA; cB = nB; ++ui;
.LBB0_220:
	s_add_u32 s50, s2, s46
	s_addc_u32 s51, s3, s47
	s_add_u32 s76, s7, s48
	s_addc_u32 s77, s11, s49
	s_andn2_b64 vcc, exec, s[74:75]
	s_cbranch_vccnz .Lzc_6242
	s_and_b64 s[8:9], s[36:37], exec
	s_cselect_b32 s10, s51, s1
	s_cselect_b32 s43, s50, s0
	s_cselect_b32 s45, s77, s39
	s_cselect_b32 vcc_lo, s76, s38
	s_add_u32 s0, s0, 0x40080
	s_addc_u32 s1, s1, 0
	s_add_u32 vcc_hi, s38, 0x100
	v_mov_b32_e32 v6, 0
	s_mov_b64 s[22:23], s[74:75]
	s_addc_u32 s8, s39, 0
	s_mov_b32 s9, 0
	v_mov_b32_e32 v7, v6
	v_mov_b32_e32 v8, v6
	v_mov_b32_e32 v9, v6
	v_mov_b32_e32 v14, v6
	v_mov_b32_e32 v15, v6
	v_mov_b32_e32 v16, v6
	v_mov_b32_e32 v17, v6
	v_mov_b32_e32 v22, v6
	v_mov_b32_e32 v23, v6
	v_mov_b32_e32 v24, v6
	v_mov_b32_e32 v25, v6
	v_mov_b32_e32 v30, v6
	v_mov_b32_e32 v31, v6
	v_mov_b32_e32 v32, v6
	v_mov_b32_e32 v33, v6
	v_mov_b32_e32 v38, v6
	v_mov_b32_e32 v39, v6
	v_mov_b32_e32 v40, v6
	v_mov_b32_e32 v41, v6
	v_mov_b32_e32 v46, v6
	v_mov_b32_e32 v47, v6
	v_mov_b32_e32 v48, v6
	v_mov_b32_e32 v49, v6
	v_mov_b32_e32 v54, v6
	v_mov_b32_e32 v55, v6
	v_mov_b32_e32 v56, v6
	v_mov_b32_e32 v57, v6
	v_mov_b32_e32 v62, v6
	v_mov_b32_e32 v63, v6
	v_mov_b32_e32 v64, v6
	v_mov_b32_e32 v65, v6
	v_mov_b32_e32 v2, v6
	v_mov_b32_e32 v3, v6
	v_mov_b32_e32 v4, v6
	v_mov_b32_e32 v5, v6
	v_mov_b32_e32 v10, v6
	v_mov_b32_e32 v11, v6
	v_mov_b32_e32 v12, v6
	v_mov_b32_e32 v13, v6
	v_mov_b32_e32 v18, v6
	v_mov_b32_e32 v19, v6
	v_mov_b32_e32 v20, v6
	v_mov_b32_e32 v21, v6
	v_mov_b32_e32 v26, v6
	v_mov_b32_e32 v27, v6
	v_mov_b32_e32 v28, v6
	v_mov_b32_e32 v29, v6
	v_mov_b32_e32 v34, v6
	v_mov_b32_e32 v35, v6
	v_mov_b32_e32 v36, v6
	v_mov_b32_e32 v37, v6
	v_mov_b32_e32 v42, v6
	v_mov_b32_e32 v43, v6
	v_mov_b32_e32 v44, v6
	v_mov_b32_e32 v45, v6
	v_mov_b32_e32 v50, v6
	v_mov_b32_e32 v51, v6
	v_mov_b32_e32 v52, v6
	v_mov_b32_e32 v53, v6
	v_mov_b32_e32 v58, v6
	v_mov_b32_e32 v59, v6
	v_mov_b32_e32 v60, v6
	v_mov_b32_e32 v61, v6
	v_mov_b32_e32 v70, v6
	v_mov_b32_e32 v71, v6
	v_mov_b32_e32 v72, v6
	v_mov_b32_e32 v73, v6
	v_mov_b32_e32 v78, v6
	v_mov_b32_e32 v79, v6
	v_mov_b32_e32 v80, v6
	v_mov_b32_e32 v81, v6
	v_mov_b32_e32 v86, v6
	v_mov_b32_e32 v87, v6
	v_mov_b32_e32 v88, v6
	v_mov_b32_e32 v89, v6
	v_mov_b32_e32 v94, v6
	v_mov_b32_e32 v95, v6
	v_mov_b32_e32 v96, v6
	v_mov_b32_e32 v97, v6
	v_mov_b32_e32 v102, v6
	v_mov_b32_e32 v103, v6
	v_mov_b32_e32 v104, v6
	v_mov_b32_e32 v105, v6
	v_mov_b32_e32 v110, v6
	v_mov_b32_e32 v111, v6
	v_mov_b32_e32 v112, v6
	v_mov_b32_e32 v113, v6
	v_mov_b32_e32 v118, v6
	v_mov_b32_e32 v119, v6
	v_mov_b32_e32 v120, v6
	v_mov_b32_e32 v121, v6
	v_mov_b32_e32 v126, v6
	v_mov_b32_e32 v127, v6
	v_mov_b32_e32 v128, v6
	v_mov_b32_e32 v129, v6
	v_mov_b32_e32 v66, v6
	v_mov_b32_e32 v67, v6
	v_mov_b32_e32 v68, v6
	v_mov_b32_e32 v69, v6
	v_mov_b32_e32 v74, v6
	v_mov_b32_e32 v75, v6
	v_mov_b32_e32 v76, v6
	v_mov_b32_e32 v77, v6
	v_mov_b32_e32 v82, v6
	v_mov_b32_e32 v83, v6
	v_mov_b32_e32 v84, v6
	v_mov_b32_e32 v85, v6
	v_mov_b32_e32 v90, v6
	v_mov_b32_e32 v91, v6
	v_mov_b32_e32 v92, v6
	v_mov_b32_e32 v93, v6
	v_mov_b32_e32 v98, v6
	v_mov_b32_e32 v99, v6
	v_mov_b32_e32 v100, v6
	v_mov_b32_e32 v101, v6
	v_mov_b32_e32 v106, v6
	v_mov_b32_e32 v107, v6
	v_mov_b32_e32 v108, v6
	v_mov_b32_e32 v109, v6
	v_mov_b32_e32 v114, v6
	v_mov_b32_e32 v115, v6
	v_mov_b32_e32 v116, v6
	v_mov_b32_e32 v117, v6
	v_mov_b32_e32 v122, v6
	v_mov_b32_e32 v123, v6
	v_mov_b32_e32 v124, v6
	v_mov_b32_e32 v125, v6

; template <class Epi, class Sched>
; __device__ __forceinline__ void gemm_phase(LAS unsigned char* lds, const Gemm g, const Sched& S, const Epi& E) {
;     ...
; #pragma unroll
;         for (int a = 0; a < 2; ++a)
; #pragma unroll
;             for (int b = 0; b < 2; ++b)
; #pragma unroll
;                 for (int m = 0; m < 4; ++m)
; #pragma unroll
;                     for (int n = 0; n < 2; ++n) acc[a][b][m][n] = (f32x4){0.f, 0.f, 0.f, 0.f};
.Lzc_6242:
	v_mov_b32_e32 v125, 0
	v_mov_b32_e32 v124, v125
	v_mov_b32_e32 v123, v125
	v_mov_b32_e32 v122, v125
	v_mov_b32_e32 v117, v125
	v_mov_b32_e32 v116, v125
	v_mov_b32_e32 v115, v125
	v_mov_b32_e32 v114, v125
	v_mov_b32_e32 v109, v125
	v_mov_b32_e32 v108, v125
	v_mov_b32_e32 v107, v125
	v_mov_b32_e32 v106, v125
	v_mov_b32_e32 v101, v125
	v_mov_b32_e32 v100, v125
	v_mov_b32_e32 v99, v125
	v_mov_b32_e32 v98, v125
	v_mov_b32_e32 v93, v125
	v_mov_b32_e32 v92, v125
	v_mov_b32_e32 v91, v125
	v_mov_b32_e32 v90, v125
	v_mov_b32_e32 v85, v125
	v_mov_b32_e32 v84, v125
	v_mov_b32_e32 v83, v125
	v_mov_b32_e32 v82, v125
	v_mov_b32_e32 v77, v125
	v_mov_b32_e32 v76, v125
	v_mov_b32_e32 v75, v125
	v_mov_b32_e32 v74, v125
	v_mov_b32_e32 v69, v125
	v_mov_b32_e32 v68, v125
	v_mov_b32_e32 v67, v125
	v_mov_b32_e32 v66, v125
	v_mov_b32_e32 v129, v125
	v_mov_b32_e32 v128, v125
	v_mov_b32_e32 v127, v125
	v_mov_b32_e32 v126, v125
	v_mov_b32_e32 v121, v125
	v_mov_b32_e32 v120, v125
	v_mov_b32_e32 v119, v125
	v_mov_b32_e32 v118, v125
	v_mov_b32_e32 v113, v125
	v_mov_b32_e32 v112, v125
	v_mov_b32_e32 v111, v125
	v_mov_b32_e32 v110, v125
	v_mov_b32_e32 v105, v125
	v_mov_b32_e32 v104, v125
	v_mov_b32_e32 v103, v125
	v_mov_b32_e32 v102, v125
	v_mov_b32_e32 v97, v125
	v_mov_b32_e32 v96, v125
	v_mov_b32_e32 v95, v125
	v_mov_b32_e32 v94, v125
	v_mov_b32_e32 v89, v125
	v_mov_b32_e32 v88, v125
	v_mov_b32_e32 v87, v125
	v_mov_b32_e32 v86, v125
	v_mov_b32_e32 v81, v125
	v_mov_b32_e32 v80, v125
	v_mov_b32_e32 v79, v125
	v_mov_b32_e32 v78, v125
	v_mov_b32_e32 v73, v125
	v_mov_b32_e32 v72, v125
	v_mov_b32_e32 v71, v125
	v_mov_b32_e32 v70, v125
	v_mov_b32_e32 v61, v125
	v_mov_b32_e32 v60, v125
	v_mov_b32_e32 v59, v125
	v_mov_b32_e32 v58, v125
	v_mov_b32_e32 v53, v125
	v_mov_b32_e32 v52, v125
	v_mov_b32_e32 v51, v125
	v_mov_b32_e32 v50, v125
	v_mov_b32_e32 v45, v125
	v_mov_b32_e32 v44, v125
	v_mov_b32_e32 v43, v125
	v_mov_b32_e32 v42, v125
	v_mov_b32_e32 v37, v125
	v_mov_b32_e32 v36, v125
	v_mov_b32_e32 v35, v125
	v_mov_b32_e32 v34, v125
	v_mov_b32_e32 v29, v125
	v_mov_b32_e32 v28, v125
	v_mov_b32_e32 v27, v125
	v_mov_b32_e32 v26, v125
	v_mov_b32_e32 v21, v125
	v_mov_b32_e32 v20, v125
	v_mov_b32_e32 v19, v125
	v_mov_b32_e32 v18, v125
	v_mov_b32_e32 v13, v125
	v_mov_b32_e32 v12, v125
	v_mov_b32_e32 v11, v125
	v_mov_b32_e32 v10, v125
	v_mov_b32_e32 v5, v125
	v_mov_b32_e32 v4, v125
	v_mov_b32_e32 v3, v125
	v_mov_b32_e32 v2, v125
	v_mov_b32_e32 v65, v125
	v_mov_b32_e32 v64, v125
	v_mov_b32_e32 v63, v125
	v_mov_b32_e32 v62, v125
	v_mov_b32_e32 v57, v125
	v_mov_b32_e32 v56, v125
	v_mov_b32_e32 v55, v125
	v_mov_b32_e32 v54, v125
	v_mov_b32_e32 v49, v125
	v_mov_b32_e32 v48, v125
	v_mov_b32_e32 v47, v125
	v_mov_b32_e32 v46, v125
	v_mov_b32_e32 v41, v125
	v_mov_b32_e32 v40, v125
	v_mov_b32_e32 v39, v125
	v_mov_b32_e32 v38, v125
	v_mov_b32_e32 v33, v125
	v_mov_b32_e32 v32, v125
	v_mov_b32_e32 v31, v125
	v_mov_b32_e32 v30, v125
	v_mov_b32_e32 v25, v125
	v_mov_b32_e32 v24, v125
	v_mov_b32_e32 v23, v125
	v_mov_b32_e32 v22, v125
	v_mov_b32_e32 v17, v125
	v_mov_b32_e32 v16, v125
	v_mov_b32_e32 v15, v125
	v_mov_b32_e32 v14, v125
	v_mov_b32_e32 v9, v125
	v_mov_b32_e32 v8, v125
	v_mov_b32_e32 v7, v125
	v_mov_b32_e32 v6, v125
	s_branch .LBB0_224

;     __device__ bool next(int i, Unit& u) const { const int L = i * G + c; if (L >= 512) return false; u.pm = 0; u.pn = L; u.offA = 0; u.offB = (size_t)L * 256 * 256 * 2; return true; }
; template <class Epi, class Sched>
; __device__ __forceinline__ void gemm_phase(LAS unsigned char* lds, const Gemm g, const Sched& S, const Epi& E) {
;     ...
;         const bool has_next = S.next(ui + 1, nxt);
;         const char* nA = has_next ? (const char*)g.A + nxt.offA : cA; const char* nB = has_next ? (const char*)g.Bt + nxt.offB : cB;
;         for (int t = 0; t < nt; t += 2) {
;             const bool last = (t == nt - 2);
;             const char* a1 = cA + (size_t)(t + 1) * kstep;
;             const char* a2 = last ? nA : cA + (size_t)(t + 2) * kstep; const char* b2 = last ? nB : cB + (size_t)(t + 2) * kstep;
;     ...
; #pragma unroll
;         for (int a = 0; a < 2; ++a)
; #pragma unroll
;             for (int b = 0; b < 2; ++b)
; #pragma unroll
;                 for (int m = 0; m < 4; ++m)
; #pragma unroll
;                     for (int n = 0; n < 2; ++n) acc[a][b][m][n] = (f32x4){0.f, 0.f, 0.f, 0.f};
;         cur = nxt; cA = nA; cB = nB; ++ui;
.LBB0_296:
	s_add_u32 s76, s66, s50
	s_addc_u32 s77, s67, s51
	v_readlane_b32 s22, v250, 44
	s_add_u32 s34, s73, s0
	v_readlane_b32 s23, v250, 45
	s_addc_u32 s35, s74, s1
	s_andn2_b64 vcc, exec, s[22:23]
	s_cbranch_vccnz .Lzc_8429
	s_and_b64 s[38:39], s[36:37], exec
	s_mov_b32 s22, s73
	s_cselect_b32 s43, s77, s9
	s_cselect_b32 s73, s76, s8
	s_cselect_b32 s82, s35, s21
	s_cselect_b32 s83, s34, s20
	s_add_u32 s84, s20, 0x100
	v_mov_b32_e32 v2, 0
	s_mov_b32 vcc_lo, s75
	s_mov_b32 s23, s74
	s_addc_u32 s85, s21, 0
	s_mov_b32 s38, 0
	s_waitcnt lgkmcnt(0)
	v_mov_b32_e32 v3, v2
	v_mov_b32_e32 v4, v2
	v_mov_b32_e32 v5, v2
	v_mov_b32_e32 v6, v2
	v_mov_b32_e32 v7, v2
	v_mov_b32_e32 v8, v2
	v_mov_b32_e32 v9, v2
	v_mov_b32_e32 v10, v2
	v_mov_b32_e32 v11, v2
	v_mov_b32_e32 v12, v2
	v_mov_b32_e32 v13, v2
	v_mov_b32_e32 v14, v2
	v_mov_b32_e32 v15, v2
	v_mov_b32_e32 v16, v2
	v_mov_b32_e32 v17, v2
	v_mov_b32_e32 v22, v2
	v_mov_b32_e32 v23, v2
	v_mov_b32_e32 v24, v2
	v_mov_b32_e32 v25, v2
	v_mov_b32_e32 v30, v2
	v_mov_b32_e32 v31, v2
	v_mov_b32_e32 v32, v2
	v_mov_b32_e32 v33, v2
	v_mov_b32_e32 v38, v2
	v_mov_b32_e32 v39, v2
	v_mov_b32_e32 v40, v2
	v_mov_b32_e32 v41, v2
	v_mov_b32_e32 v46, v2
	v_mov_b32_e32 v47, v2
	v_mov_b32_e32 v48, v2
	v_mov_b32_e32 v49, v2
	v_mov_b32_e32 v18, v2
	v_mov_b32_e32 v19, v2
	v_mov_b32_e32 v20, v2
	v_mov_b32_e32 v21, v2
	v_mov_b32_e32 v26, v2
	v_mov_b32_e32 v27, v2
	v_mov_b32_e32 v28, v2
	v_mov_b32_e32 v29, v2
	v_mov_b32_e32 v34, v2
	v_mov_b32_e32 v35, v2
	v_mov_b32_e32 v36, v2
	v_mov_b32_e32 v37, v2
	v_mov_b32_e32 v42, v2
	v_mov_b32_e32 v43, v2
	v_mov_b32_e32 v44, v2
	v_mov_b32_e32 v45, v2
	v_mov_b32_e32 v50, v2
	v_mov_b32_e32 v51, v2
	v_mov_b32_e32 v52, v2
	v_mov_b32_e32 v53, v2
	v_mov_b32_e32 v54, v2
	v_mov_b32_e32 v55, v2
	v_mov_b32_e32 v56, v2
	v_mov_b32_e32 v57, v2
	v_mov_b32_e32 v58, v2
	v_mov_b32_e32 v59, v2
	v_mov_b32_e32 v60, v2
	v_mov_b32_e32 v61, v2
	v_mov_b32_e32 v62, v2
	v_mov_b32_e32 v63, v2
	v_mov_b32_e32 v64, v2
	v_mov_b32_e32 v65, v2
	v_mov_b32_e32 v66, v2
	v_mov_b32_e32 v67, v2
	v_mov_b32_e32 v68, v2
	v_mov_b32_e32 v69, v2
	v_mov_b32_e32 v70, v2
	v_mov_b32_e32 v71, v2
	v_mov_b32_e32 v72, v2
	v_mov_b32_e32 v73, v2
	v_mov_b32_e32 v74, v2
	v_mov_b32_e32 v75, v2
	v_mov_b32_e32 v76, v2
	v_mov_b32_e32 v77, v2
	v_mov_b32_e32 v78, v2
	v_mov_b32_e32 v79, v2
	v_mov_b32_e32 v80, v2
	v_mov_b32_e32 v81, v2
	v_mov_b32_e32 v86, v2
	v_mov_b32_e32 v87, v2
	v_mov_b32_e32 v88, v2
	v_mov_b32_e32 v89, v2
	v_mov_b32_e32 v94, v2
	v_mov_b32_e32 v95, v2
	v_mov_b32_e32 v96, v2
	v_mov_b32_e32 v97, v2
	v_mov_b32_e32 v102, v2
	v_mov_b32_e32 v103, v2
	v_mov_b32_e32 v104, v2
	v_mov_b32_e32 v105, v2
	v_mov_b32_e32 v110, v2
	v_mov_b32_e32 v111, v2
	v_mov_b32_e32 v112, v2
	v_mov_b32_e32 v113, v2
	v_mov_b32_e32 v82, v2
	v_mov_b32_e32 v83, v2
	v_mov_b32_e32 v84, v2
	v_mov_b32_e32 v85, v2
	v_mov_b32_e32 v90, v2
	v_mov_b32_e32 v91, v2
	v_mov_b32_e32 v92, v2
	v_mov_b32_e32 v93, v2
	v_mov_b32_e32 v98, v2
	v_mov_b32_e32 v99, v2
	v_mov_b32_e32 v100, v2
	v_mov_b32_e32 v101, v2
	v_mov_b32_e32 v106, v2
	v_mov_b32_e32 v107, v2
	v_mov_b32_e32 v108, v2
	v_mov_b32_e32 v109, v2
	v_mov_b32_e32 v114, v2
	v_mov_b32_e32 v115, v2
	v_mov_b32_e32 v116, v2
	v_mov_b32_e32 v117, v2
	v_mov_b32_e32 v118, v2
	v_mov_b32_e32 v119, v2
	v_mov_b32_e32 v120, v2
	v_mov_b32_e32 v121, v2
	v_mov_b32_e32 v122, v2
	v_mov_b32_e32 v123, v2
	v_mov_b32_e32 v124, v2
	v_mov_b32_e32 v125, v2
	v_mov_b32_e32 v126, v2
	v_mov_b32_e32 v127, v2
	v_mov_b32_e32 v128, v2
	v_mov_b32_e32 v129, v2

; template <class Epi, class Sched>
; __device__ __forceinline__ void gemm_phase(LAS unsigned char* lds, const Gemm g, const Sched& S, const Epi& E) {
;     ...
; #pragma unroll
;         for (int a = 0; a < 2; ++a)
; #pragma unroll
;             for (int b = 0; b < 2; ++b)
; #pragma unroll
;                 for (int m = 0; m < 4; ++m)
; #pragma unroll
;                     for (int n = 0; n < 2; ++n) acc[a][b][m][n] = (f32x4){0.f, 0.f, 0.f, 0.f};
.Lzc_8429:
	v_mov_b32_e32 v183, 0
	v_mov_b32_e32 v182, v183
	v_mov_b32_e32 v185, v183
	v_mov_b32_e32 v184, v183
	v_mov_b32_e32 v187, v183
	v_mov_b32_e32 v186, v183
	v_mov_b32_e32 v189, v183
	v_mov_b32_e32 v188, v183
	v_mov_b32_e32 v171, v183
	v_mov_b32_e32 v170, v183
	v_mov_b32_e32 v169, v183
	v_mov_b32_e32 v168, v183
	v_mov_b32_e32 v167, v183
	v_mov_b32_e32 v166, v183
	v_mov_b32_e32 v165, v183
	v_mov_b32_e32 v164, v183
	v_mov_b32_e32 v151, v183
	v_mov_b32_e32 v150, v183
	v_mov_b32_e32 v149, v183
	v_mov_b32_e32 v148, v183
	v_mov_b32_e32 v147, v183
	v_mov_b32_e32 v146, v183
	v_mov_b32_e32 v145, v183
	v_mov_b32_e32 v144, v183
	v_mov_b32_e32 v125, v183
	v_mov_b32_e32 v124, v183
	v_mov_b32_e32 v123, v183
	v_mov_b32_e32 v122, v183
	v_mov_b32_e32 v121, v183
	v_mov_b32_e32 v120, v183
	v_mov_b32_e32 v119, v183
	v_mov_b32_e32 v118, v183
	v_mov_b32_e32 v181, v183
	v_mov_b32_e32 v180, v183
	v_mov_b32_e32 v179, v183
	v_mov_b32_e32 v178, v183
	v_mov_b32_e32 v177, v183
	v_mov_b32_e32 v176, v183
	v_mov_b32_e32 v175, v183
	v_mov_b32_e32 v174, v183
	v_mov_b32_e32 v163, v183
	v_mov_b32_e32 v162, v183
	v_mov_b32_e32 v161, v183
	v_mov_b32_e32 v160, v183
	v_mov_b32_e32 v159, v183
	v_mov_b32_e32 v158, v183
	v_mov_b32_e32 v157, v183
	v_mov_b32_e32 v156, v183
	v_mov_b32_e32 v143, v183
	v_mov_b32_e32 v142, v183
	v_mov_b32_e32 v141, v183
	v_mov_b32_e32 v140, v183
	v_mov_b32_e32 v129, v183
	v_mov_b32_e32 v128, v183
	v_mov_b32_e32 v127, v183
	v_mov_b32_e32 v126, v183
	v_mov_b32_e32 v117, v183
	v_mov_b32_e32 v116, v183
	v_mov_b32_e32 v115, v183
	v_mov_b32_e32 v114, v183
	v_mov_b32_e32 v113, v183
	v_mov_b32_e32 v112, v183
	v_mov_b32_e32 v111, v183
	v_mov_b32_e32 v110, v183
	v_mov_b32_e32 v103, v183
	v_mov_b32_e32 v102, v183
	v_mov_b32_e32 v105, v183
	v_mov_b32_e32 v104, v183
	v_mov_b32_e32 v107, v183
	v_mov_b32_e32 v106, v183
	v_mov_b32_e32 v109, v183
	v_mov_b32_e32 v108, v183
	v_mov_b32_e32 v93, v183
	v_mov_b32_e32 v92, v183
	v_mov_b32_e32 v91, v183
	v_mov_b32_e32 v90, v183
	v_mov_b32_e32 v89, v183
	v_mov_b32_e32 v88, v183
	v_mov_b32_e32 v87, v183
	v_mov_b32_e32 v86, v183
	v_mov_b32_e32 v73, v183
	v_mov_b32_e32 v72, v183
	v_mov_b32_e32 v71, v183
	v_mov_b32_e32 v70, v183
	v_mov_b32_e32 v69, v183
	v_mov_b32_e32 v68, v183
	v_mov_b32_e32 v67, v183
	v_mov_b32_e32 v66, v183
	v_mov_b32_e32 v57, v183
	v_mov_b32_e32 v56, v183
	v_mov_b32_e32 v55, v183
	v_mov_b32_e32 v54, v183
	v_mov_b32_e32 v53, v183
	v_mov_b32_e32 v52, v183
	v_mov_b32_e32 v51, v183
	v_mov_b32_e32 v50, v183
	v_mov_b32_e32 v101, v183
	v_mov_b32_e32 v100, v183
	v_mov_b32_e32 v99, v183
	v_mov_b32_e32 v98, v183
	v_mov_b32_e32 v97, v183
	v_mov_b32_e32 v96, v183
	v_mov_b32_e32 v95, v183
	v_mov_b32_e32 v94, v183
	v_mov_b32_e32 v83, v183
	v_mov_b32_e32 v82, v183
	v_mov_b32_e32 v81, v183
	v_mov_b32_e32 v80, v183
	v_mov_b32_e32 v79, v183
	v_mov_b32_e32 v78, v183
	v_mov_b32_e32 v77, v183
	v_mov_b32_e32 v76, v183
	v_mov_b32_e32 v65, v183
	v_mov_b32_e32 v64, v183
	v_mov_b32_e32 v63, v183
	v_mov_b32_e32 v62, v183
	v_mov_b32_e32 v61, v183
	v_mov_b32_e32 v60, v183
	v_mov_b32_e32 v59, v183
	v_mov_b32_e32 v58, v183
	v_mov_b32_e32 v49, v183
	v_mov_b32_e32 v48, v183
	v_mov_b32_e32 v47, v183
	v_mov_b32_e32 v46, v183
	v_mov_b32_e32 v45, v183
	v_mov_b32_e32 v44, v183
	v_mov_b32_e32 v43, v183
	v_mov_b32_e32 v42, v183
	s_branch .LBB0_300

;     __device__ bool next(int i, Unit& u) const { const int L = i * G + c; if (L >= 512) return false; u.pm = 0; u.pn = L; u.offA = 0; u.offB = (size_t)L * 256 * 256 * 2; return true; }
; template <class Epi, class Sched>
; __device__ __forceinline__ void gemm_phase(LAS unsigned char* lds, const Gemm g, const Sched& S, const Epi& E) {
;     ...
;         const bool has_next = S.next(ui + 1, nxt);
;         const char* nA = has_next ? (const char*)g.A + nxt.offA : cA; const char* nB = has_next ? (const char*)g.Bt + nxt.offB : cB;
;         for (int t = 0; t < nt; t += 2) {
;             const bool last = (t == nt - 2);
;             const char* a1 = cA + (size_t)(t + 1) * kstep;
;             const char* a2 = last ? nA : cA + (size_t)(t + 2) * kstep; const char* b2 = last ? nB : cB + (size_t)(t + 2) * kstep;
;     ...
; #pragma unroll
;         for (int a = 0; a < 2; ++a)
; #pragma unroll
;             for (int b = 0; b < 2; ++b)
; #pragma unroll
;                 for (int m = 0; m < 4; ++m)
; #pragma unroll
;                     for (int n = 0; n < 2; ++n) acc[a][b][m][n] = (f32x4){0.f, 0.f, 0.f, 0.f};
;         cur = nxt; cA = nA; cB = nB; ++ui;
.LBB0_483:
	s_add_u32 s76, s2, s50
	s_addc_u32 s77, s3, s51
	v_readlane_b32 s8, v254, 4
	v_readlane_b32 s9, v254, 5
	s_add_u32 s8, s8, s36
	s_addc_u32 s9, s9, s37
	s_andn2_b64 vcc, exec, s[34:35]
	s_cbranch_vccnz .Lzc_11212
	s_and_b64 s[42:43], s[20:21], exec
	s_cselect_b32 s47, s77, s39
	s_cselect_b32 s49, s76, s38
	s_cselect_b32 s73, s9, s41
	s_cselect_b32 s82, s8, s40
	s_add_u32 s38, s38, 0x40080
	s_addc_u32 s39, s39, 0
	s_add_u32 s83, s40, 0x100
	v_mov_b32_e32 v6, 0
	s_addc_u32 s84, s41, 0
	s_mov_b32 s40, 0
	v_mov_b32_e32 v7, v6
	v_mov_b32_e32 v8, v6
	v_mov_b32_e32 v9, v6
	v_mov_b32_e32 v14, v6
	v_mov_b32_e32 v15, v6
	v_mov_b32_e32 v16, v6
	v_mov_b32_e32 v17, v6
	v_mov_b32_e32 v22, v6
	v_mov_b32_e32 v23, v6
	v_mov_b32_e32 v24, v6
	v_mov_b32_e32 v25, v6
	v_mov_b32_e32 v26, v6
	v_mov_b32_e32 v27, v6
	v_mov_b32_e32 v28, v6
	v_mov_b32_e32 v29, v6
	v_mov_b32_e32 v38, v6
	v_mov_b32_e32 v39, v6
	v_mov_b32_e32 v40, v6
	v_mov_b32_e32 v41, v6
	v_mov_b32_e32 v42, v6
	v_mov_b32_e32 v43, v6
	v_mov_b32_e32 v44, v6
	v_mov_b32_e32 v45, v6
	v_mov_b32_e32 v54, v6
	v_mov_b32_e32 v55, v6
	v_mov_b32_e32 v56, v6
	v_mov_b32_e32 v57, v6
	v_mov_b32_e32 v58, v6
	v_mov_b32_e32 v59, v6
	v_mov_b32_e32 v60, v6
	v_mov_b32_e32 v61, v6
	v_mov_b32_e32 v2, v6
	v_mov_b32_e32 v3, v6
	v_mov_b32_e32 v4, v6
	v_mov_b32_e32 v5, v6
	v_mov_b32_e32 v10, v6
	v_mov_b32_e32 v11, v6
	v_mov_b32_e32 v12, v6
	v_mov_b32_e32 v13, v6
	v_mov_b32_e32 v18, v6
	v_mov_b32_e32 v19, v6
	v_mov_b32_e32 v20, v6
	v_mov_b32_e32 v21, v6
	v_mov_b32_e32 v30, v6
	v_mov_b32_e32 v31, v6
	v_mov_b32_e32 v32, v6
	v_mov_b32_e32 v33, v6
	v_mov_b32_e32 v34, v6
	v_mov_b32_e32 v35, v6
	v_mov_b32_e32 v36, v6
	v_mov_b32_e32 v37, v6
	v_mov_b32_e32 v46, v6
	v_mov_b32_e32 v47, v6
	v_mov_b32_e32 v48, v6
	v_mov_b32_e32 v49, v6
	v_mov_b32_e32 v50, v6
	v_mov_b32_e32 v51, v6
	v_mov_b32_e32 v52, v6
	v_mov_b32_e32 v53, v6
	v_mov_b32_e32 v62, v6
	v_mov_b32_e32 v63, v6
	v_mov_b32_e32 v64, v6
	v_mov_b32_e32 v65, v6
	v_mov_b32_e32 v70, v6
	v_mov_b32_e32 v71, v6
	v_mov_b32_e32 v72, v6
	v_mov_b32_e32 v73, v6
	v_mov_b32_e32 v74, v6
	v_mov_b32_e32 v75, v6
	v_mov_b32_e32 v76, v6
	v_mov_b32_e32 v77, v6
	v_mov_b32_e32 v86, v6
	v_mov_b32_e32 v87, v6
	v_mov_b32_e32 v88, v6
	v_mov_b32_e32 v89, v6
	v_mov_b32_e32 v90, v6
	v_mov_b32_e32 v91, v6
	v_mov_b32_e32 v92, v6
	v_mov_b32_e32 v93, v6
	v_mov_b32_e32 v102, v6
	v_mov_b32_e32 v103, v6
	v_mov_b32_e32 v104, v6
	v_mov_b32_e32 v105, v6
	v_mov_b32_e32 v106, v6
	v_mov_b32_e32 v107, v6
	v_mov_b32_e32 v108, v6
	v_mov_b32_e32 v109, v6
	v_mov_b32_e32 v118, v6
	v_mov_b32_e32 v119, v6
	v_mov_b32_e32 v120, v6
	v_mov_b32_e32 v121, v6
	v_mov_b32_e32 v126, v6
	v_mov_b32_e32 v127, v6
	v_mov_b32_e32 v128, v6
	v_mov_b32_e32 v129, v6
	v_mov_b32_e32 v66, v6
	v_mov_b32_e32 v67, v6
	v_mov_b32_e32 v68, v6
	v_mov_b32_e32 v69, v6
	v_mov_b32_e32 v78, v6
	v_mov_b32_e32 v79, v6
	v_mov_b32_e32 v80, v6
	v_mov_b32_e32 v81, v6
	v_mov_b32_e32 v82, v6
	v_mov_b32_e32 v83, v6
	v_mov_b32_e32 v84, v6
	v_mov_b32_e32 v85, v6
	v_mov_b32_e32 v94, v6
	v_mov_b32_e32 v95, v6
	v_mov_b32_e32 v96, v6
	v_mov_b32_e32 v97, v6
	v_mov_b32_e32 v98, v6
	v_mov_b32_e32 v99, v6
	v_mov_b32_e32 v100, v6
	v_mov_b32_e32 v101, v6
	v_mov_b32_e32 v110, v6
	v_mov_b32_e32 v111, v6
	v_mov_b32_e32 v112, v6
	v_mov_b32_e32 v113, v6
	v_mov_b32_e32 v114, v6
	v_mov_b32_e32 v115, v6
	v_mov_b32_e32 v116, v6
	v_mov_b32_e32 v117, v6
	v_mov_b32_e32 v122, v6
	v_mov_b32_e32 v123, v6
	v_mov_b32_e32 v124, v6
	v_mov_b32_e32 v125, v6

; template <class Epi, class Sched>
; __device__ __forceinline__ void gemm_phase(LAS unsigned char* lds, const Gemm g, const Sched& S, const Epi& E) {
;     ...
; #pragma unroll
;         for (int a = 0; a < 2; ++a)
; #pragma unroll
;             for (int b = 0; b < 2; ++b)
; #pragma unroll
;                 for (int m = 0; m < 4; ++m)
; #pragma unroll
;                     for (int n = 0; n < 2; ++n) acc[a][b][m][n] = (f32x4){0.f, 0.f, 0.f, 0.f};
.Lzc_11212:
	v_mov_b32_e32 v125, 0
	v_mov_b32_e32 v124, v125
	v_mov_b32_e32 v123, v125
	v_mov_b32_e32 v122, v125
	v_mov_b32_e32 v117, v125
	v_mov_b32_e32 v116, v125
	v_mov_b32_e32 v115, v125
	v_mov_b32_e32 v114, v125
	v_mov_b32_e32 v113, v125
	v_mov_b32_e32 v112, v125
	v_mov_b32_e32 v111, v125
	v_mov_b32_e32 v110, v125
	v_mov_b32_e32 v101, v125
	v_mov_b32_e32 v100, v125
	v_mov_b32_e32 v99, v125
	v_mov_b32_e32 v98, v125
	v_mov_b32_e32 v97, v125
	v_mov_b32_e32 v96, v125
	v_mov_b32_e32 v95, v125
	v_mov_b32_e32 v94, v125
	v_mov_b32_e32 v85, v125
	v_mov_b32_e32 v84, v125
	v_mov_b32_e32 v83, v125
	v_mov_b32_e32 v82, v125
	v_mov_b32_e32 v81, v125
	v_mov_b32_e32 v80, v125
	v_mov_b32_e32 v79, v125
	v_mov_b32_e32 v78, v125
	v_mov_b32_e32 v69, v125
	v_mov_b32_e32 v68, v125
	v_mov_b32_e32 v67, v125
	v_mov_b32_e32 v66, v125
	v_mov_b32_e32 v129, v125
	v_mov_b32_e32 v128, v125
	v_mov_b32_e32 v127, v125
	v_mov_b32_e32 v126, v125
	v_mov_b32_e32 v121, v125
	v_mov_b32_e32 v120, v125
	v_mov_b32_e32 v119, v125
	v_mov_b32_e32 v118, v125
	v_mov_b32_e32 v109, v125
	v_mov_b32_e32 v108, v125
	v_mov_b32_e32 v107, v125
	v_mov_b32_e32 v106, v125
	v_mov_b32_e32 v105, v125
	v_mov_b32_e32 v104, v125
	v_mov_b32_e32 v103, v125
	v_mov_b32_e32 v102, v125
	v_mov_b32_e32 v93, v125
	v_mov_b32_e32 v92, v125
	v_mov_b32_e32 v91, v125
	v_mov_b32_e32 v90, v125
	v_mov_b32_e32 v89, v125
	v_mov_b32_e32 v88, v125
	v_mov_b32_e32 v87, v125
	v_mov_b32_e32 v86, v125
	v_mov_b32_e32 v77, v125
	v_mov_b32_e32 v76, v125
	v_mov_b32_e32 v75, v125
	v_mov_b32_e32 v74, v125
	v_mov_b32_e32 v73, v125
	v_mov_b32_e32 v72, v125
	v_mov_b32_e32 v71, v125
	v_mov_b32_e32 v70, v125
	v_mov_b32_e32 v65, v125
	v_mov_b32_e32 v64, v125
	v_mov_b32_e32 v63, v125
	v_mov_b32_e32 v62, v125
	v_mov_b32_e32 v53, v125
	v_mov_b32_e32 v52, v125
	v_mov_b32_e32 v51, v125
	v_mov_b32_e32 v50, v125
	v_mov_b32_e32 v49, v125
	v_mov_b32_e32 v48, v125
	v_mov_b32_e32 v47, v125
	v_mov_b32_e32 v46, v125
	v_mov_b32_e32 v37, v125
	v_mov_b32_e32 v36, v125
	v_mov_b32_e32 v35, v125
	v_mov_b32_e32 v34, v125
	v_mov_b32_e32 v33, v125
	v_mov_b32_e32 v32, v125
	v_mov_b32_e32 v31, v125
	v_mov_b32_e32 v30, v125
	v_mov_b32_e32 v21, v125
	v_mov_b32_e32 v20, v125
	v_mov_b32_e32 v19, v125
	v_mov_b32_e32 v18, v125
	v_mov_b32_e32 v13, v125
	v_mov_b32_e32 v12, v125
	v_mov_b32_e32 v11, v125
	v_mov_b32_e32 v10, v125
	v_mov_b32_e32 v5, v125
	v_mov_b32_e32 v4, v125
	v_mov_b32_e32 v3, v125
	v_mov_b32_e32 v2, v125
	v_mov_b32_e32 v61, v125
	v_mov_b32_e32 v60, v125
	v_mov_b32_e32 v59, v125
	v_mov_b32_e32 v58, v125
	v_mov_b32_e32 v57, v125
	v_mov_b32_e32 v56, v125
	v_mov_b32_e32 v55, v125
	v_mov_b32_e32 v54, v125
	v_mov_b32_e32 v45, v125
	v_mov_b32_e32 v44, v125
	v_mov_b32_e32 v43, v125
	v_mov_b32_e32 v42, v125
	v_mov_b32_e32 v41, v125
	v_mov_b32_e32 v40, v125
	v_mov_b32_e32 v39, v125
	v_mov_b32_e32 v38, v125
	v_mov_b32_e32 v29, v125
	v_mov_b32_e32 v28, v125
	v_mov_b32_e32 v27, v125
	v_mov_b32_e32 v26, v125
	v_mov_b32_e32 v25, v125
	v_mov_b32_e32 v24, v125
	v_mov_b32_e32 v23, v125
	v_mov_b32_e32 v22, v125
	v_mov_b32_e32 v17, v125
	v_mov_b32_e32 v16, v125
	v_mov_b32_e32 v15, v125
	v_mov_b32_e32 v14, v125
	v_mov_b32_e32 v9, v125
	v_mov_b32_e32 v8, v125
	v_mov_b32_e32 v7, v125
	v_mov_b32_e32 v6, v125
	s_branch .LBB0_486

;     __device__ bool next(int i, Unit& u) const { const int L = i * G + c; if (L >= 512) return false; u.pm = 0; u.pn = L; u.offA = 0; u.offB = (size_t)L * 256 * 256 * 2; return true; }
; template <class Epi, class Sched>
; __device__ __forceinline__ void gemm_phase(LAS unsigned char* lds, const Gemm g, const Sched& S, const Epi& E) {
;     ...
;         const bool has_next = S.next(ui + 1, nxt);
;         const char* nA = has_next ? (const char*)g.A + nxt.offA : cA; const char* nB = has_next ? (const char*)g.Bt + nxt.offB : cB;
;         for (int t = 0; t < nt; t += 2) {
;             const bool last = (t == nt - 2);
;             const char* a1 = cA + (size_t)(t + 1) * kstep;
;             const char* a2 = last ? nA : cA + (size_t)(t + 2) * kstep; const char* b2 = last ? nB : cB + (size_t)(t + 2) * kstep;
;     ...
; #pragma unroll
;         for (int a = 0; a < 2; ++a)
; #pragma unroll
;             for (int b = 0; b < 2; ++b)
; #pragma unroll
;                 for (int m = 0; m < 4; ++m)
; #pragma unroll
;                     for (int n = 0; n < 2; ++n) acc[a][b][m][n] = (f32x4){0.f, 0.f, 0.f, 0.f};
;         cur = nxt; cA = nA; cB = nB; ++ui;
.LBB0_534:
	v_readlane_b32 s22, v251, 29
	v_readlane_b32 s23, v251, 30
	s_add_u32 s40, s22, s34
	s_addc_u32 s41, s23, s35
	s_add_u32 s42, s2, s36
	s_addc_u32 s43, s3, s37
	s_andn2_b64 vcc, exec, s[8:9]
	s_cbranch_vccnz .Lzc_13474
	s_and_b64 s[76:77], s[38:39], exec
	s_cselect_b32 s73, s41, s45
	s_cselect_b32 s76, s40, s44
	s_cselect_b32 s77, s43, s47
	s_cselect_b32 s78, s42, s46
	s_add_u32 s44, s44, 0x40080
	s_addc_u32 s45, s45, 0
	s_add_u32 s80, s46, 0x100
	v_mov_b32_e32 v2, 0
	s_addc_u32 s82, s47, 0
	s_mov_b32 s46, 0
	v_mov_b32_e32 v3, v2
	v_mov_b32_e32 v4, v2
	v_mov_b32_e32 v5, v2
	v_mov_b32_e32 v6, v2
	v_mov_b32_e32 v7, v2
	v_mov_b32_e32 v8, v2
	v_mov_b32_e32 v9, v2
	v_mov_b32_e32 v18, v2
	v_mov_b32_e32 v19, v2
	v_mov_b32_e32 v20, v2
	v_mov_b32_e32 v21, v2
	v_mov_b32_e32 v22, v2
	v_mov_b32_e32 v23, v2
	v_mov_b32_e32 v24, v2
	v_mov_b32_e32 v25, v2
	v_mov_b32_e32 v34, v2
	v_mov_b32_e32 v35, v2
	v_mov_b32_e32 v36, v2
	v_mov_b32_e32 v37, v2
	v_mov_b32_e32 v38, v2
	v_mov_b32_e32 v39, v2
	v_mov_b32_e32 v40, v2
	v_mov_b32_e32 v41, v2
	v_mov_b32_e32 v50, v2
	v_mov_b32_e32 v51, v2
	v_mov_b32_e32 v52, v2
	v_mov_b32_e32 v53, v2
	v_mov_b32_e32 v54, v2
	v_mov_b32_e32 v55, v2
	v_mov_b32_e32 v56, v2
	v_mov_b32_e32 v57, v2
	v_mov_b32_e32 v10, v2
	v_mov_b32_e32 v11, v2
	v_mov_b32_e32 v12, v2
	v_mov_b32_e32 v13, v2
	v_mov_b32_e32 v14, v2
	v_mov_b32_e32 v15, v2
	v_mov_b32_e32 v16, v2
	v_mov_b32_e32 v17, v2
	v_mov_b32_e32 v26, v2
	v_mov_b32_e32 v27, v2
	v_mov_b32_e32 v28, v2
	v_mov_b32_e32 v29, v2
	v_mov_b32_e32 v30, v2
	v_mov_b32_e32 v31, v2
	v_mov_b32_e32 v32, v2
	v_mov_b32_e32 v33, v2
	v_mov_b32_e32 v42, v2
	v_mov_b32_e32 v43, v2
	v_mov_b32_e32 v44, v2
	v_mov_b32_e32 v45, v2
	v_mov_b32_e32 v46, v2
	v_mov_b32_e32 v47, v2
	v_mov_b32_e32 v48, v2
	v_mov_b32_e32 v49, v2
	v_mov_b32_e32 v58, v2
	v_mov_b32_e32 v59, v2
	v_mov_b32_e32 v60, v2
	v_mov_b32_e32 v61, v2
	v_mov_b32_e32 v62, v2
	v_mov_b32_e32 v63, v2
	v_mov_b32_e32 v64, v2
	v_mov_b32_e32 v65, v2
	v_mov_b32_e32 v66, v2
	v_mov_b32_e32 v67, v2
	v_mov_b32_e32 v68, v2
	v_mov_b32_e32 v69, v2
	v_mov_b32_e32 v70, v2
	v_mov_b32_e32 v71, v2
	v_mov_b32_e32 v72, v2
	v_mov_b32_e32 v73, v2
	v_mov_b32_e32 v82, v2
	v_mov_b32_e32 v83, v2
	v_mov_b32_e32 v84, v2
	v_mov_b32_e32 v85, v2
	v_mov_b32_e32 v86, v2
	v_mov_b32_e32 v87, v2
	v_mov_b32_e32 v88, v2
	v_mov_b32_e32 v89, v2
	v_mov_b32_e32 v98, v2
	v_mov_b32_e32 v99, v2
	v_mov_b32_e32 v100, v2
	v_mov_b32_e32 v101, v2
	v_mov_b32_e32 v102, v2
	v_mov_b32_e32 v103, v2
	v_mov_b32_e32 v104, v2
	v_mov_b32_e32 v105, v2
	v_mov_b32_e32 v114, v2
	v_mov_b32_e32 v115, v2
	v_mov_b32_e32 v116, v2
	v_mov_b32_e32 v117, v2
	v_mov_b32_e32 v118, v2
	v_mov_b32_e32 v119, v2
	v_mov_b32_e32 v120, v2
	v_mov_b32_e32 v121, v2
	v_mov_b32_e32 v74, v2
	v_mov_b32_e32 v75, v2
	v_mov_b32_e32 v76, v2
	v_mov_b32_e32 v77, v2
	v_mov_b32_e32 v78, v2
	v_mov_b32_e32 v79, v2
	v_mov_b32_e32 v80, v2
	v_mov_b32_e32 v81, v2
	v_mov_b32_e32 v90, v2
	v_mov_b32_e32 v91, v2
	v_mov_b32_e32 v92, v2
	v_mov_b32_e32 v93, v2
	v_mov_b32_e32 v94, v2
	v_mov_b32_e32 v95, v2
	v_mov_b32_e32 v96, v2
	v_mov_b32_e32 v97, v2
	v_mov_b32_e32 v106, v2
	v_mov_b32_e32 v107, v2
	v_mov_b32_e32 v108, v2
	v_mov_b32_e32 v109, v2
	v_mov_b32_e32 v110, v2
	v_mov_b32_e32 v111, v2
	v_mov_b32_e32 v112, v2
	v_mov_b32_e32 v113, v2
	v_mov_b32_e32 v126, v2
	v_mov_b32_e32 v127, v2
	v_mov_b32_e32 v128, v2
	v_mov_b32_e32 v129, v2
	v_mov_b32_e32 v122, v2
	v_mov_b32_e32 v123, v2
	v_mov_b32_e32 v124, v2
	v_mov_b32_e32 v125, v2
	s_mov_b64 s[22:23], 0x800
	s_mov_b64 vcc, 0x880

; template <class Epi, class Sched>
; __device__ __forceinline__ void gemm_phase(LAS unsigned char* lds, const Gemm g, const Sched& S, const Epi& E) {
;     ...
; #pragma unroll
;         for (int a = 0; a < 2; ++a)
; #pragma unroll
;             for (int b = 0; b < 2; ++b)
; #pragma unroll
;                 for (int m = 0; m < 4; ++m)
; #pragma unroll
;                     for (int n = 0; n < 2; ++n) acc[a][b][m][n] = (f32x4){0.f, 0.f, 0.f, 0.f};
.Lzc_13474:
	v_mov_b32_e32 v125, 0
	v_mov_b32_e32 v124, v125
	v_mov_b32_e32 v123, v125
	v_mov_b32_e32 v122, v125
	v_mov_b32_e32 v129, v125
	v_mov_b32_e32 v128, v125
	v_mov_b32_e32 v127, v125
	v_mov_b32_e32 v126, v125
	v_mov_b32_e32 v113, v125
	v_mov_b32_e32 v112, v125
	v_mov_b32_e32 v111, v125
	v_mov_b32_e32 v110, v125
	v_mov_b32_e32 v109, v125
	v_mov_b32_e32 v108, v125
	v_mov_b32_e32 v107, v125
	v_mov_b32_e32 v106, v125
	v_mov_b32_e32 v97, v125
	v_mov_b32_e32 v96, v125
	v_mov_b32_e32 v95, v125
	v_mov_b32_e32 v94, v125
	v_mov_b32_e32 v93, v125
	v_mov_b32_e32 v92, v125
	v_mov_b32_e32 v91, v125
	v_mov_b32_e32 v90, v125
	v_mov_b32_e32 v81, v125
	v_mov_b32_e32 v80, v125
	v_mov_b32_e32 v79, v125
	v_mov_b32_e32 v78, v125
	v_mov_b32_e32 v77, v125
	v_mov_b32_e32 v76, v125
	v_mov_b32_e32 v75, v125
	v_mov_b32_e32 v74, v125
	v_mov_b32_e32 v121, v125
	v_mov_b32_e32 v120, v125
	v_mov_b32_e32 v119, v125
	v_mov_b32_e32 v118, v125
	v_mov_b32_e32 v117, v125
	v_mov_b32_e32 v116, v125
	v_mov_b32_e32 v115, v125
	v_mov_b32_e32 v114, v125
	v_mov_b32_e32 v105, v125
	v_mov_b32_e32 v104, v125
	v_mov_b32_e32 v103, v125
	v_mov_b32_e32 v102, v125
	v_mov_b32_e32 v101, v125
	v_mov_b32_e32 v100, v125
	v_mov_b32_e32 v99, v125
	v_mov_b32_e32 v98, v125
	v_mov_b32_e32 v89, v125
	v_mov_b32_e32 v88, v125
	v_mov_b32_e32 v87, v125
	v_mov_b32_e32 v86, v125
	v_mov_b32_e32 v85, v125
	v_mov_b32_e32 v84, v125
	v_mov_b32_e32 v83, v125
	v_mov_b32_e32 v82, v125
	v_mov_b32_e32 v73, v125
	v_mov_b32_e32 v72, v125
	v_mov_b32_e32 v71, v125
	v_mov_b32_e32 v70, v125
	v_mov_b32_e32 v69, v125
	v_mov_b32_e32 v68, v125
	v_mov_b32_e32 v67, v125
	v_mov_b32_e32 v66, v125
	v_mov_b32_e32 v65, v125
	v_mov_b32_e32 v64, v125
	v_mov_b32_e32 v63, v125
	v_mov_b32_e32 v62, v125
	v_mov_b32_e32 v61, v125
	v_mov_b32_e32 v60, v125
	v_mov_b32_e32 v59, v125
	v_mov_b32_e32 v58, v125
	v_mov_b32_e32 v49, v125
	v_mov_b32_e32 v48, v125
	v_mov_b32_e32 v47, v125
	v_mov_b32_e32 v46, v125
	v_mov_b32_e32 v45, v125
	v_mov_b32_e32 v44, v125
	v_mov_b32_e32 v43, v125
	v_mov_b32_e32 v42, v125
	v_mov_b32_e32 v33, v125
	v_mov_b32_e32 v32, v125
	v_mov_b32_e32 v31, v125
	v_mov_b32_e32 v30, v125
	v_mov_b32_e32 v29, v125
	v_mov_b32_e32 v28, v125
	v_mov_b32_e32 v27, v125
	v_mov_b32_e32 v26, v125
	v_mov_b32_e32 v17, v125
	v_mov_b32_e32 v16, v125
	v_mov_b32_e32 v15, v125
	v_mov_b32_e32 v14, v125
	v_mov_b32_e32 v13, v125
	v_mov_b32_e32 v12, v125
	v_mov_b32_e32 v11, v125
	v_mov_b32_e32 v10, v125
	v_mov_b32_e32 v57, v125
	v_mov_b32_e32 v56, v125
	v_mov_b32_e32 v55, v125
	v_mov_b32_e32 v54, v125
	v_mov_b32_e32 v53, v125
	v_mov_b32_e32 v52, v125
	v_mov_b32_e32 v51, v125
	v_mov_b32_e32 v50, v125
	v_mov_b32_e32 v41, v125
	v_mov_b32_e32 v40, v125
	v_mov_b32_e32 v39, v125
	v_mov_b32_e32 v38, v125
	v_mov_b32_e32 v37, v125
	v_mov_b32_e32 v36, v125
	v_mov_b32_e32 v35, v125
	v_mov_b32_e32 v34, v125
	v_mov_b32_e32 v25, v125
	v_mov_b32_e32 v24, v125
	v_mov_b32_e32 v23, v125
	v_mov_b32_e32 v22, v125
	v_mov_b32_e32 v21, v125
	v_mov_b32_e32 v20, v125
	v_mov_b32_e32 v19, v125
	v_mov_b32_e32 v18, v125
	v_mov_b32_e32 v9, v125
	v_mov_b32_e32 v8, v125
	v_mov_b32_e32 v7, v125
	v_mov_b32_e32 v6, v125
	v_mov_b32_e32 v5, v125
	v_mov_b32_e32 v4, v125
	v_mov_b32_e32 v3, v125
	v_mov_b32_e32 v2, v125
	s_branch .LBB0_538

; #define LAS __attribute__((address_space(3)))
; __device__ __forceinline__ u32x4 pack8(f32x4 a, f32x4 b) { u32x4 w; w.x = cvt_pk_bf16(a[0], a[1]); w.y = cvt_pk_bf16(a[2], a[3]); w.z = cvt_pk_bf16(b[0], b[1]); w.w = cvt_pk_bf16(b[2], b[3]); return w; }
; __device__ __forceinline__ void attn_unit(LAS unsigned char* lds, const bf16_t* qkv, bf16_t* ao, const float* qg, const float* kg, const float* sink, int b, int nb, int kvh, int S) {
;     ...
;     LAS bf16_t* Ks = (LAS bf16_t*)lds;
;     LAS bf16_t* Vt = (LAS bf16_t*)(lds + 384 * KP * 2);
;     for (int i = tid; i < 64 * 24; i += 512) { const int d = i / 24, cc = 384 + i % 24; Vt[d * VP + cc] = 0; }
; #pragma unroll 1
;     for (int it = 0; it < 6; ++it) { const int i = tid + 512 * it; const int key = i >> 3, ch = i & 7; const int s = nb * 128 - 128 + key; const bool ok = (s >= 0 && s < S);
;         u32x4 kw = (u32x4){0u, 0u, 0u, 0u}, vw = (u32x4){0u, 0u, 0u, 0u};
;         if (ok) { const bf16_t* p = qkv + ((size_t)b * S + s) * 768 + 512 + kvh * 64 + ch * 8; kw = *(const u32x4*)p; vw = *(const u32x4*)(p + 128); }
;         f32x4 k0, k1; unpack8(kw, k0, k1);
;         float ss = (k0[0] * k0[0] + k0[1] * k0[1]) + (k0[2] * k0[2] + k0[3] * k0[3]) + (k1[0] * k1[0] + k1[1] * k1[1]) + (k1[2] * k1[2] + k1[3] * k1[3]);
;         ss += __shfl_xor(ss, 1); ss += __shfl_xor(ss, 2); ss += __shfl_xor(ss, 4);
;         const float rk = rsqrtf(ss * (1.0f / 64.0f) + EPS);
;         const f32x4 g0 = *(const f32x4*)(kg + ch * 8), g1 = *(const f32x4*)(kg + ch * 8 + 4);
;         *(LAS u32x4*)(Ks + key * KP + ch * 8) = pack8(k0 * g0 * rk, k1 * g1 * rk);
.LBB0_614:
	s_or_b64 exec, exec, s[8:9]
	s_ashr_i32 s1, s7, 1
	s_abs_i32 s8, s1
	v_readlane_b32 s9, v250, 32
	s_mul_hi_u32 s9, s8, s9
	s_mul_i32 s12, s9, s97
	v_and_b32_e32 v3, 64, v235
	s_sub_i32 s8, s8, s12
	v_xor_b32_e32 v0, 1, v235
	v_add_u32_e32 v3, 64, v3
	s_and_b32 s11, s7, 1
	s_ashr_i32 s0, s7, 31
	s_add_i32 s12, s9, 1
	s_sub_i32 s16, s8, s97
	v_cmp_lt_i32_e32 vcc, v0, v3
	s_cmp_ge_u32 s8, s97
	s_cselect_b32 s9, s12, s9
	v_cndmask_b32_e32 v0, v235, v0, vcc
	v_lshlrev_b32_e32 v15, 2, v0
	v_xor_b32_e32 v0, 2, v235
	s_cselect_b32 s8, s16, s8
	s_add_i32 s12, s9, 1
	v_cmp_lt_i32_e32 vcc, v0, v3
	s_cmp_ge_u32 s8, s97
	s_cselect_b32 s8, s12, s9
	v_cndmask_b32_e32 v0, v235, v0, vcc
	v_lshlrev_b32_e32 v18, 2, v0
	v_xor_b32_e32 v0, 4, v235
	s_xor_b32 s8, s8, s0
	v_cmp_lt_i32_e32 vcc, v0, v3
	s_sub_i32 s0, s8, s0
	s_mul_i32 s8, s0, s97
	v_cndmask_b32_e32 v0, v235, v0, vcc
	v_lshlrev_b32_e32 v19, 2, v0
	v_lshlrev_b32_e32 v0, 3, v2
	s_sub_i32 s16, s1, s8
	v_and_b32_e32 v4, 56, v0
	v_readlane_b32 s8, v254, 53
	v_lshlrev_b32_e32 v0, 2, v4
	v_readlane_b32 s9, v254, 54
	s_ashr_i32 s1, s0, 31
	s_lshl_b32 s12, s16, 7
	v_lshl_add_u64 v[12:13], s[8:9], 0, v[0:1]
	v_lshlrev_b32_e32 v0, 1, v4
	v_readlane_b32 s8, v250, 29
	v_add_u32_e32 v14, 0, v0
	s_lshl_b64 s[36:37], s[0:1], s8
	s_movk_i32 s0, 0x32e
	s_add_i32 s20, s12, 0xffffff80
	v_mad_u32_u24 v20, v4, s0, v14
	s_lshl_b32 s0, s11, 7
	s_add_u32 s0, s66, s0
	s_addc_u32 s1, s67, 0
	s_mov_b32 s21, 0
	v_lshl_add_u64 v[16:17], s[0:1], 0, v[0:1]
	global_load_dwordx4 v[114:117], v[12:13], off offset:16
	global_load_dwordx4 v[110:113], v[12:13], off
	v_mov_b32_e32 v119, 0
	v_mov_b32_e32 v118, v2
	v_ashrrev_i32_e32 v118, 3, v118
	v_add_u32_e32 v118, s20, v118
	v_cmp_gt_u32_e32 vcc, s27, v118
	v_mov_b32_e32 v62, 0
	v_mov_b32_e32 v63, 0
	v_mov_b32_e32 v64, 0
	v_mov_b32_e32 v65, 0
	v_mov_b32_e32 v86, 0
	v_mov_b32_e32 v87, 0
	v_mov_b32_e32 v88, 0
	v_mov_b32_e32 v89, 0
	s_and_saveexec_b64 s[8:9], vcc
	s_cbranch_execz .Lattn_pf0
	v_lshl_add_u64 v[120:121], s[36:37], 0, v[118:119]
	v_mad_u64_u32 v[122:123], s[0:1], v120, s29, v[16:17]
	v_mad_i32_i24 v123, v121, s29, v123
	global_load_dwordx4 v[62:65], v[122:123], off offset:1024
	global_load_dwordx4 v[86:89], v[122:123], off offset:1280
.Lattn_pf0:
	s_or_b64 exec, exec, s[8:9]
	v_add_u32_e32 v118, 0x200, v2
	v_ashrrev_i32_e32 v118, 3, v118
	v_add_u32_e32 v118, s20, v118
	v_cmp_gt_u32_e32 vcc, s27, v118
	v_mov_b32_e32 v66, 0
	v_mov_b32_e32 v67, 0
	v_mov_b32_e32 v68, 0
	v_mov_b32_e32 v69, 0
	v_mov_b32_e32 v90, 0
	v_mov_b32_e32 v91, 0
	v_mov_b32_e32 v92, 0
	v_mov_b32_e32 v93, 0
	s_and_saveexec_b64 s[8:9], vcc
	s_cbranch_execz .Lattn_pf1
	v_lshl_add_u64 v[120:121], s[36:37], 0, v[118:119]
	v_mad_u64_u32 v[122:123], s[0:1], v120, s29, v[16:17]
	v_mad_i32_i24 v123, v121, s29, v123
	global_load_dwordx4 v[66:69], v[122:123], off offset:1024
	global_load_dwordx4 v[90:93], v[122:123], off offset:1280
.Lattn_pf1:
	s_or_b64 exec, exec, s[8:9]
	v_add_u32_e32 v118, 0x400, v2
	v_ashrrev_i32_e32 v118, 3, v118
	v_add_u32_e32 v118, s20, v118
	v_cmp_gt_u32_e32 vcc, s27, v118
	v_mov_b32_e32 v70, 0
	v_mov_b32_e32 v71, 0
	v_mov_b32_e32 v72, 0
	v_mov_b32_e32 v73, 0
	v_mov_b32_e32 v94, 0
	v_mov_b32_e32 v95, 0
	v_mov_b32_e32 v96, 0
	v_mov_b32_e32 v97, 0
	s_and_saveexec_b64 s[8:9], vcc
	s_cbranch_execz .Lattn_pf2
	v_lshl_add_u64 v[120:121], s[36:37], 0, v[118:119]
	v_mad_u64_u32 v[122:123], s[0:1], v120, s29, v[16:17]
	v_mad_i32_i24 v123, v121, s29, v123
	global_load_dwordx4 v[70:73], v[122:123], off offset:1024
	global_load_dwordx4 v[94:97], v[122:123], off offset:1280
.Lattn_pf2:
	s_or_b64 exec, exec, s[8:9]
	v_add_u32_e32 v118, 0x600, v2
	v_ashrrev_i32_e32 v118, 3, v118
	v_add_u32_e32 v118, s20, v118
	v_cmp_gt_u32_e32 vcc, s27, v118
	v_mov_b32_e32 v74, 0
	v_mov_b32_e32 v75, 0
	v_mov_b32_e32 v76, 0
	v_mov_b32_e32 v77, 0
	v_mov_b32_e32 v98, 0
	v_mov_b32_e32 v99, 0
	v_mov_b32_e32 v100, 0
	v_mov_b32_e32 v101, 0
	s_and_saveexec_b64 s[8:9], vcc
	s_cbranch_execz .Lattn_pf3
	v_lshl_add_u64 v[120:121], s[36:37], 0, v[118:119]
	v_mad_u64_u32 v[122:123], s[0:1], v120, s29, v[16:17]
	v_mad_i32_i24 v123, v121, s29, v123
	global_load_dwordx4 v[74:77], v[122:123], off offset:1024
	global_load_dwordx4 v[98:101], v[122:123], off offset:1280
; #define LAS __attribute__((address_space(3)))
; __device__ __forceinline__ u32x4 pack8(f32x4 a, f32x4 b) { u32x4 w; w.x = cvt_pk_bf16(a[0], a[1]); w.y = cvt_pk_bf16(a[2], a[3]); w.z = cvt_pk_bf16(b[0], b[1]); w.w = cvt_pk_bf16(b[2], b[3]); return w; }
; __device__ __forceinline__ void attn_unit(LAS unsigned char* lds, const bf16_t* qkv, bf16_t* ao, const float* qg, const float* kg, const float* sink, int b, int nb, int kvh, int S) {
;     ...
;     for (int it = 0; it < 6; ++it) { const int i = tid + 512 * it; const int key = i >> 3, ch = i & 7; const int s = nb * 128 - 128 + key; const bool ok = (s >= 0 && s < S);
;         u32x4 kw = (u32x4){0u, 0u, 0u, 0u}, vw = (u32x4){0u, 0u, 0u, 0u};
;         if (ok) { const bf16_t* p = qkv + ((size_t)b * S + s) * 768 + 512 + kvh * 64 + ch * 8; kw = *(const u32x4*)p; vw = *(const u32x4*)(p + 128); }
;         f32x4 k0, k1; unpack8(kw, k0, k1);
;         float ss = (k0[0] * k0[0] + k0[1] * k0[1]) + (k0[2] * k0[2] + k0[3] * k0[3]) + (k1[0] * k1[0] + k1[1] * k1[1]) + (k1[2] * k1[2] + k1[3] * k1[3]);
;         ss += __shfl_xor(ss, 1); ss += __shfl_xor(ss, 2); ss += __shfl_xor(ss, 4);
;         const float rk = rsqrtf(ss * (1.0f / 64.0f) + EPS);
;         const f32x4 g0 = *(const f32x4*)(kg + ch * 8), g1 = *(const f32x4*)(kg + ch * 8 + 4);
;         *(LAS u32x4*)(Ks + key * KP + ch * 8) = pack8(k0 * g0 * rk, k1 * g1 * rk);
;         const unsigned vv[4] = {vw.x, vw.y, vw.z, vw.w};
; #pragma unroll
;         for (int e = 0; e < 4; ++e) { Vt[(ch * 8 + 2 * e) * VP + key] = (bf16_t)(vv[e] & 0xffffu); Vt[(ch * 8 + 2 * e + 1) * VP + key] = (bf16_t)(vv[e] >> 16); }
;     }
.Lattn_pf3:
	s_or_b64 exec, exec, s[8:9]
	v_add_u32_e32 v118, 0x800, v2
	v_ashrrev_i32_e32 v118, 3, v118
	v_add_u32_e32 v118, s20, v118
	v_cmp_gt_u32_e32 vcc, s27, v118
	v_mov_b32_e32 v78, 0
	v_mov_b32_e32 v79, 0
	v_mov_b32_e32 v80, 0
	v_mov_b32_e32 v81, 0
	v_mov_b32_e32 v102, 0
	v_mov_b32_e32 v103, 0
	v_mov_b32_e32 v104, 0
	v_mov_b32_e32 v105, 0
	s_and_saveexec_b64 s[8:9], vcc
	s_cbranch_execz .Lattn_pf4
	v_lshl_add_u64 v[120:121], s[36:37], 0, v[118:119]
	v_mad_u64_u32 v[122:123], s[0:1], v120, s29, v[16:17]
	v_mad_i32_i24 v123, v121, s29, v123
	global_load_dwordx4 v[78:81], v[122:123], off offset:1024
	global_load_dwordx4 v[102:105], v[122:123], off offset:1280
.Lattn_pf4:
	s_or_b64 exec, exec, s[8:9]
	v_add_u32_e32 v118, 0xa00, v2
	v_ashrrev_i32_e32 v118, 3, v118
	v_add_u32_e32 v118, s20, v118
	v_cmp_gt_u32_e32 vcc, s27, v118
	v_mov_b32_e32 v82, 0
	v_mov_b32_e32 v83, 0
	v_mov_b32_e32 v84, 0
	v_mov_b32_e32 v85, 0
	v_mov_b32_e32 v106, 0
	v_mov_b32_e32 v107, 0
	v_mov_b32_e32 v108, 0
	v_mov_b32_e32 v109, 0
	s_and_saveexec_b64 s[8:9], vcc
	s_cbranch_execz .Lattn_pf5
	v_lshl_add_u64 v[120:121], s[36:37], 0, v[118:119]
	v_mad_u64_u32 v[122:123], s[0:1], v120, s29, v[16:17]
	v_mad_i32_i24 v123, v121, s29, v123
	global_load_dwordx4 v[82:85], v[122:123], off offset:1024
	global_load_dwordx4 v[106:109], v[122:123], off offset:1280
.Lattn_pf5:
	s_or_b64 exec, exec, s[8:9]
	s_branch .LBB0_616
.LBB0_615:
	s_waitcnt vmcnt(0)
	v_and_b32_e32 v29, 0xffff0000, v9
	v_and_b32_e32 v28, 0xffff0000, v8
	v_lshlrev_b32_e32 v27, 16, v9
	v_lshlrev_b32_e32 v26, 16, v8
	v_pk_mul_f32 v[8:9], v[28:29], v[28:29]
	v_and_b32_e32 v33, 0xffff0000, v11
	v_and_b32_e32 v32, 0xffff0000, v10
	v_pk_fma_f32 v[8:9], v[26:27], v[26:27], v[8:9]
	v_lshlrev_b32_e32 v31, 16, v11
	v_lshlrev_b32_e32 v30, 16, v10
	v_pk_mul_f32 v[10:11], v[32:33], v[32:33]
	v_add_f32_e32 v0, v8, v9
	v_pk_fma_f32 v[10:11], v[30:31], v[30:31], v[10:11]
	v_mov_b32_e32 v34, v26
	v_add_f32_e32 v0, v10, v0
	v_add_f32_e32 v0, v11, v0
	ds_bpermute_b32 v8, v15, v0
	v_mov_b32_e32 v35, v28
	v_mov_b32_e32 v28, v27
	v_mov_b32_e32 v26, v30
	v_mov_b32_e32 v27, v32
	s_waitcnt lgkmcnt(0)
	v_add_f32_e32 v0, v0, v8
	ds_bpermute_b32 v8, v18, v0
	v_mov_b32_e32 v32, v31
	s_addk_i32 s21, 0x200
	s_cmpk_eq_i32 s21, 0xc00
	s_waitcnt lgkmcnt(0)
	v_add_f32_e32 v0, v0, v8
	ds_bpermute_b32 v8, v19, v0
	s_waitcnt lgkmcnt(0)
	v_add_f32_e32 v0, v0, v8
	v_fmamk_f32 v0, v0, 0x3c800000, v192
	v_cmp_gt_f32_e32 vcc, s93, v0
	v_mul_f32_e32 v8, 0x4b800000, v0
	s_nop 0
	v_cndmask_b32_e32 v0, v0, v8, vcc
	v_rsq_f32_e32 v0, v0
	s_nop 0
	v_mul_f32_e32 v8, 0x45800000, v0
	v_cndmask_b32_e32 v0, v0, v8, vcc
	v_pk_mul_f32 v[8:9], v[114:115], v[26:27]
	v_pk_mul_f32 v[22:23], v[110:111], v[34:35]
	v_pk_mul_f32 v[24:25], v[112:113], v[28:29]
	v_pk_mul_f32 v[22:23], v[22:23], v[0:1] op_sel_hi:[1,0]
	v_pk_mul_f32 v[10:11], v[116:117], v[32:33]
	v_pk_mul_f32 v[24:25], v[24:25], v[0:1] op_sel_hi:[1,0]
	v_pk_mul_f32 v[26:27], v[10:11], v[0:1] op_sel_hi:[1,0]
	v_pk_mul_f32 v[10:11], v[8:9], v[0:1] op_sel_hi:[1,0]
	v_cvt_pk_bf16_f32 v8, v22, v23
	v_mad_u64_u32 v[22:23], s[0:1], v21, s61, v[14:15]
	v_lshl_add_u32 v0, v21, 1, v20
	v_cvt_pk_bf16_f32 v9, v24, v25
	v_cvt_pk_bf16_f32 v10, v10, v11
	v_cvt_pk_bf16_f32 v11, v26, v27
	ds_write_b128 v22, v[8:11]
	ds_write_b16 v0, v4 offset:55296
	ds_write_b16_d16_hi v0, v4 offset:56112
	ds_write_b16 v0, v5 offset:56928
	ds_write_b16_d16_hi v0, v5 offset:57744
	ds_write_b16 v0, v6 offset:58560
	ds_write_b16_d16_hi v0, v6 offset:59376
	ds_write_b16 v0, v7 offset:60192
	ds_write_b16_d16_hi v0, v7 offset:61008
	s_cbranch_scc1 .LBB0_618
.LBB0_616:
	v_add_u32_e32 v0, s21, v2
	v_ashrrev_i32_e32 v21, 3, v0
	s_waitcnt vmcnt(0)
	v_mov_b32_e32 v8, v62
	v_mov_b32_e32 v9, v63
	v_mov_b32_e32 v10, v64
	v_mov_b32_e32 v11, v65
	v_mov_b32_e32 v4, v86
	v_mov_b32_e32 v5, v87
	v_mov_b32_e32 v6, v88
	v_mov_b32_e32 v7, v89
	v_mov_b64_e32 v[62:63], v[66:67]
	v_mov_b64_e32 v[64:65], v[68:69]
	v_mov_b64_e32 v[66:67], v[70:71]
	v_mov_b64_e32 v[68:69], v[72:73]
	v_mov_b64_e32 v[70:71], v[74:75]
	v_mov_b64_e32 v[72:73], v[76:77]
	v_mov_b64_e32 v[74:75], v[78:79]
	v_mov_b64_e32 v[76:77], v[80:81]
	v_mov_b64_e32 v[78:79], v[82:83]
	v_mov_b64_e32 v[80:81], v[84:85]
	v_mov_b64_e32 v[86:87], v[90:91]
	v_mov_b64_e32 v[88:89], v[92:93]
	v_mov_b64_e32 v[90:91], v[94:95]
	v_mov_b64_e32 v[92:93], v[96:97]
	v_mov_b64_e32 v[94:95], v[98:99]
	v_mov_b64_e32 v[96:97], v[100:101]
	v_mov_b64_e32 v[98:99], v[102:103]
	v_mov_b64_e32 v[100:101], v[104:105]
	v_mov_b64_e32 v[102:103], v[106:107]
	v_mov_b64_e32 v[104:105], v[108:109]
	s_branch .LBB0_615

;     __device__ bool next(int i, Unit& u) const { const int L = i * G + c; if (L >= 512) return false; u.pm = 0; u.pn = L; u.offA = 0; u.offB = (size_t)L * 256 * 256 * 2; return true; }
; template <class Epi, class Sched>
; __device__ __forceinline__ void gemm_phase(LAS unsigned char* lds, const Gemm g, const Sched& S, const Epi& E) {
;     ...
;         const bool has_next = S.next(ui + 1, nxt);
;         const char* nA = has_next ? (const char*)g.A + nxt.offA : cA; const char* nB = has_next ? (const char*)g.Bt + nxt.offB : cB;
;         for (int t = 0; t < nt; t += 2) {
;             const bool last = (t == nt - 2);
;             const char* a1 = cA + (size_t)(t + 1) * kstep;
;             const char* a2 = last ? nA : cA + (size_t)(t + 2) * kstep; const char* b2 = last ? nB : cB + (size_t)(t + 2) * kstep;
;     ...
; #pragma unroll
;         for (int a = 0; a < 2; ++a)
; #pragma unroll
;             for (int b = 0; b < 2; ++b)
; #pragma unroll
;                 for (int m = 0; m < 4; ++m)
; #pragma unroll
;                     for (int n = 0; n < 2; ++n) acc[a][b][m][n] = (f32x4){0.f, 0.f, 0.f, 0.f};
;         cur = nxt; cA = nA; cB = nB; ++ui;
.LBB0_635:
	s_add_u32 s38, s68, s36
	s_addc_u32 s39, s69, s37
	s_andn2_b64 vcc, exec, s[20:21]
	s_cbranch_vccnz .Lzc_17144
	s_and_b64 s[0:1], s[40:41], exec
	s_cselect_b32 s73, s39, s43
	s_cselect_b32 s76, s38, s42
	s_add_u32 s77, s42, 0x100
	v_mov_b32_e32 v2, 0
	s_addc_u32 s78, s43, 0
	s_mov_b32 s46, 0
	s_mov_b64 s[42:43], 0
	v_mov_b32_e32 v3, v2
	v_mov_b32_e32 v4, v2
	v_mov_b32_e32 v5, v2
	v_mov_b32_e32 v10, v2
	v_mov_b32_e32 v11, v2
	v_mov_b32_e32 v12, v2
	v_mov_b32_e32 v13, v2
	v_mov_b32_e32 v34, v2
	v_mov_b32_e32 v35, v2
	v_mov_b32_e32 v36, v2
	v_mov_b32_e32 v37, v2
	v_mov_b32_e32 v42, v2
	v_mov_b32_e32 v43, v2
	v_mov_b32_e32 v44, v2
	v_mov_b32_e32 v45, v2
	v_mov_b32_e32 v66, v2
	v_mov_b32_e32 v67, v2
	v_mov_b32_e32 v68, v2
	v_mov_b32_e32 v69, v2
	v_mov_b32_e32 v74, v2
	v_mov_b32_e32 v75, v2
	v_mov_b32_e32 v76, v2
	v_mov_b32_e32 v77, v2
	v_mov_b32_e32 v98, v2
	v_mov_b32_e32 v99, v2
	v_mov_b32_e32 v100, v2
	v_mov_b32_e32 v101, v2
	v_mov_b32_e32 v106, v2
	v_mov_b32_e32 v107, v2
	v_mov_b32_e32 v108, v2
	v_mov_b32_e32 v109, v2
	v_mov_b32_e32 v18, v2
	v_mov_b32_e32 v19, v2
	v_mov_b32_e32 v20, v2
	v_mov_b32_e32 v21, v2
	v_mov_b32_e32 v26, v2
	v_mov_b32_e32 v27, v2
	v_mov_b32_e32 v28, v2
	v_mov_b32_e32 v29, v2
	v_mov_b32_e32 v50, v2
	v_mov_b32_e32 v51, v2
	v_mov_b32_e32 v52, v2
	v_mov_b32_e32 v53, v2
	v_mov_b32_e32 v58, v2
	v_mov_b32_e32 v59, v2
	v_mov_b32_e32 v60, v2
	v_mov_b32_e32 v61, v2
	v_mov_b32_e32 v82, v2
	v_mov_b32_e32 v83, v2
	v_mov_b32_e32 v84, v2
	v_mov_b32_e32 v85, v2
	v_mov_b32_e32 v90, v2
	v_mov_b32_e32 v91, v2
	v_mov_b32_e32 v92, v2
	v_mov_b32_e32 v93, v2
	v_mov_b32_e32 v114, v2
	v_mov_b32_e32 v115, v2
	v_mov_b32_e32 v116, v2
	v_mov_b32_e32 v117, v2
	v_mov_b32_e32 v122, v2
	v_mov_b32_e32 v123, v2
	v_mov_b32_e32 v124, v2
	v_mov_b32_e32 v125, v2
	v_mov_b32_e32 v6, v2
	v_mov_b32_e32 v7, v2
	v_mov_b32_e32 v8, v2
	v_mov_b32_e32 v9, v2
	v_mov_b32_e32 v14, v2
	v_mov_b32_e32 v15, v2
	v_mov_b32_e32 v16, v2
	v_mov_b32_e32 v17, v2
	v_mov_b32_e32 v38, v2
	v_mov_b32_e32 v39, v2
	v_mov_b32_e32 v40, v2
	v_mov_b32_e32 v41, v2
	v_mov_b32_e32 v46, v2
	v_mov_b32_e32 v47, v2
	v_mov_b32_e32 v48, v2
	v_mov_b32_e32 v49, v2
	v_mov_b32_e32 v70, v2
	v_mov_b32_e32 v71, v2
	v_mov_b32_e32 v72, v2
	v_mov_b32_e32 v73, v2
	v_mov_b32_e32 v78, v2
	v_mov_b32_e32 v79, v2
	v_mov_b32_e32 v80, v2
	v_mov_b32_e32 v81, v2
	v_mov_b32_e32 v102, v2
	v_mov_b32_e32 v103, v2
	v_mov_b32_e32 v104, v2
	v_mov_b32_e32 v105, v2
	v_mov_b32_e32 v110, v2
	v_mov_b32_e32 v111, v2
	v_mov_b32_e32 v112, v2
	v_mov_b32_e32 v113, v2
	v_mov_b32_e32 v22, v2
	v_mov_b32_e32 v23, v2
	v_mov_b32_e32 v24, v2
	v_mov_b32_e32 v25, v2
	v_mov_b32_e32 v30, v2
	v_mov_b32_e32 v31, v2
	v_mov_b32_e32 v32, v2
	v_mov_b32_e32 v33, v2
	v_mov_b32_e32 v54, v2
	v_mov_b32_e32 v55, v2
	v_mov_b32_e32 v56, v2
	v_mov_b32_e32 v57, v2
	v_mov_b32_e32 v62, v2
	v_mov_b32_e32 v63, v2
	v_mov_b32_e32 v64, v2
	v_mov_b32_e32 v65, v2
	v_mov_b32_e32 v86, v2
	v_mov_b32_e32 v87, v2
	v_mov_b32_e32 v88, v2
	v_mov_b32_e32 v89, v2
	v_mov_b32_e32 v94, v2
	v_mov_b32_e32 v95, v2
	v_mov_b32_e32 v96, v2
	v_mov_b32_e32 v97, v2
	v_mov_b32_e32 v118, v2
	v_mov_b32_e32 v119, v2
	v_mov_b32_e32 v120, v2
	v_mov_b32_e32 v121, v2
	v_mov_b32_e32 v126, v2
	v_mov_b32_e32 v127, v2
	v_mov_b32_e32 v128, v2
	v_mov_b32_e32 v129, v2

; template <class Epi, class Sched>
; __device__ __forceinline__ void gemm_phase(LAS unsigned char* lds, const Gemm g, const Sched& S, const Epi& E) {
;     ...
; #pragma unroll
;         for (int a = 0; a < 2; ++a)
; #pragma unroll
;             for (int b = 0; b < 2; ++b)
; #pragma unroll
;                 for (int m = 0; m < 4; ++m)
; #pragma unroll
;                     for (int n = 0; n < 2; ++n) acc[a][b][m][n] = (f32x4){0.f, 0.f, 0.f, 0.f};
.Lzc_17144:
	v_mov_b32_e32 v129, 0
	v_mov_b32_e32 v128, v129
	v_mov_b32_e32 v127, v129
	v_mov_b32_e32 v126, v129
	v_mov_b32_e32 v121, v129
	v_mov_b32_e32 v120, v129
	v_mov_b32_e32 v119, v129
	v_mov_b32_e32 v118, v129
	v_mov_b32_e32 v97, v129
	v_mov_b32_e32 v96, v129
	v_mov_b32_e32 v95, v129
	v_mov_b32_e32 v94, v129
	v_mov_b32_e32 v89, v129
	v_mov_b32_e32 v88, v129
	v_mov_b32_e32 v87, v129
	v_mov_b32_e32 v86, v129
	v_mov_b32_e32 v65, v129
	v_mov_b32_e32 v64, v129
	v_mov_b32_e32 v63, v129
	v_mov_b32_e32 v62, v129
	v_mov_b32_e32 v57, v129
	v_mov_b32_e32 v56, v129
	v_mov_b32_e32 v55, v129
	v_mov_b32_e32 v54, v129
	v_mov_b32_e32 v33, v129
	v_mov_b32_e32 v32, v129
	v_mov_b32_e32 v31, v129
	v_mov_b32_e32 v30, v129
	v_mov_b32_e32 v25, v129
	v_mov_b32_e32 v24, v129
	v_mov_b32_e32 v23, v129
	v_mov_b32_e32 v22, v129
	v_mov_b32_e32 v113, v129
	v_mov_b32_e32 v112, v129
	v_mov_b32_e32 v111, v129
	v_mov_b32_e32 v110, v129
	v_mov_b32_e32 v105, v129
	v_mov_b32_e32 v104, v129
	v_mov_b32_e32 v103, v129
	v_mov_b32_e32 v102, v129
	v_mov_b32_e32 v81, v129
	v_mov_b32_e32 v80, v129
	v_mov_b32_e32 v79, v129
	v_mov_b32_e32 v78, v129
	v_mov_b32_e32 v73, v129
	v_mov_b32_e32 v72, v129
	v_mov_b32_e32 v71, v129
	v_mov_b32_e32 v70, v129
	v_mov_b32_e32 v49, v129
	v_mov_b32_e32 v48, v129
	v_mov_b32_e32 v47, v129
	v_mov_b32_e32 v46, v129
	v_mov_b32_e32 v41, v129
	v_mov_b32_e32 v40, v129
	v_mov_b32_e32 v39, v129
	v_mov_b32_e32 v38, v129
	v_mov_b32_e32 v17, v129
	v_mov_b32_e32 v16, v129
	v_mov_b32_e32 v15, v129
	v_mov_b32_e32 v14, v129
	v_mov_b32_e32 v9, v129
	v_mov_b32_e32 v8, v129
	v_mov_b32_e32 v7, v129
	v_mov_b32_e32 v6, v129
	v_mov_b32_e32 v125, v129
	v_mov_b32_e32 v124, v129
	v_mov_b32_e32 v123, v129
	v_mov_b32_e32 v122, v129
	v_mov_b32_e32 v117, v129
	v_mov_b32_e32 v116, v129
	v_mov_b32_e32 v115, v129
	v_mov_b32_e32 v114, v129
	v_mov_b32_e32 v93, v129
	v_mov_b32_e32 v92, v129
	v_mov_b32_e32 v91, v129
	v_mov_b32_e32 v90, v129
	v_mov_b32_e32 v85, v129
	v_mov_b32_e32 v84, v129
	v_mov_b32_e32 v83, v129
	v_mov_b32_e32 v82, v129
	v_mov_b32_e32 v61, v129
	v_mov_b32_e32 v60, v129
	v_mov_b32_e32 v59, v129
	v_mov_b32_e32 v58, v129
	v_mov_b32_e32 v53, v129
	v_mov_b32_e32 v52, v129
	v_mov_b32_e32 v51, v129
	v_mov_b32_e32 v50, v129
	v_mov_b32_e32 v29, v129
	v_mov_b32_e32 v28, v129
	v_mov_b32_e32 v27, v129
	v_mov_b32_e32 v26, v129
	v_mov_b32_e32 v21, v129
	v_mov_b32_e32 v20, v129
	v_mov_b32_e32 v19, v129
	v_mov_b32_e32 v18, v129
	v_mov_b32_e32 v109, v129
	v_mov_b32_e32 v108, v129
	v_mov_b32_e32 v107, v129
	v_mov_b32_e32 v106, v129
	v_mov_b32_e32 v101, v129
	v_mov_b32_e32 v100, v129
	v_mov_b32_e32 v99, v129
	v_mov_b32_e32 v98, v129
	v_mov_b32_e32 v77, v129
	v_mov_b32_e32 v76, v129
	v_mov_b32_e32 v75, v129
	v_mov_b32_e32 v74, v129
	v_mov_b32_e32 v69, v129
	v_mov_b32_e32 v68, v129
	v_mov_b32_e32 v67, v129
	v_mov_b32_e32 v66, v129
	v_mov_b32_e32 v45, v129
	v_mov_b32_e32 v44, v129
	v_mov_b32_e32 v43, v129
	v_mov_b32_e32 v42, v129
	v_mov_b32_e32 v37, v129
	v_mov_b32_e32 v36, v129
	v_mov_b32_e32 v35, v129
	v_mov_b32_e32 v34, v129
	v_mov_b32_e32 v13, v129
	v_mov_b32_e32 v12, v129
	v_mov_b32_e32 v11, v129
	v_mov_b32_e32 v10, v129
	v_mov_b32_e32 v5, v129
	v_mov_b32_e32 v4, v129
	v_mov_b32_e32 v3, v129
	v_mov_b32_e32 v2, v129
	s_branch .LBB0_638

;     __device__ bool next(int i, Unit& u) const { const int L = i * G + c; if (L >= 512) return false; u.pm = 0; u.pn = L; u.offA = 0; u.offB = (size_t)L * 256 * 256 * 2; return true; }
; template <class Epi, class Sched>
; __device__ __forceinline__ void gemm_phase(LAS unsigned char* lds, const Gemm g, const Sched& S, const Epi& E) {
;     ...
;         const bool has_next = S.next(ui + 1, nxt);
;         const char* nA = has_next ? (const char*)g.A + nxt.offA : cA; const char* nB = has_next ? (const char*)g.Bt + nxt.offB : cB;
;         for (int t = 0; t < nt; t += 2) {
;             const bool last = (t == nt - 2);
;             const char* a1 = cA + (size_t)(t + 1) * kstep;
;             const char* a2 = last ? nA : cA + (size_t)(t + 2) * kstep; const char* b2 = last ? nB : cB + (size_t)(t + 2) * kstep;
;     ...
; #pragma unroll
;         for (int a = 0; a < 2; ++a)
; #pragma unroll
;             for (int b = 0; b < 2; ++b)
; #pragma unroll
;                 for (int m = 0; m < 4; ++m)
; #pragma unroll
;                     for (int n = 0; n < 2; ++n) acc[a][b][m][n] = (f32x4){0.f, 0.f, 0.f, 0.f};
;         cur = nxt; cA = nA; cB = nB; ++ui;
.LBB0_658:
	s_add_u32 s8, s2, s50
	s_addc_u32 s9, s3, s51
	v_readlane_b32 s0, v254, 4
	v_readlane_b32 s1, v254, 5
	s_add_u32 s20, s0, s76
	s_addc_u32 s21, s1, s77
	s_andn2_b64 vcc, exec, s[34:35]
	s_cbranch_vccnz .Lzc_19087
	s_and_b64 s[0:1], s[38:39], exec
	s_cselect_b32 s47, s9, s37
	s_cselect_b32 s49, s8, s36
	s_cselect_b32 s83, s21, s41
	s_cselect_b32 vcc_lo, s20, s40
	s_add_u32 s36, s36, 0x40080
	s_addc_u32 s37, s37, 0
	s_add_u32 vcc_hi, s40, 0x100
	v_mov_b32_e32 v6, 0
	s_addc_u32 s96, s41, 0
	s_mov_b32 s40, 0
	v_mov_b32_e32 v7, v6
	v_mov_b32_e32 v8, v6
	v_mov_b32_e32 v9, v6
	v_mov_b32_e32 v14, v6
	v_mov_b32_e32 v15, v6
	v_mov_b32_e32 v16, v6
	v_mov_b32_e32 v17, v6
	v_mov_b32_e32 v22, v6
	v_mov_b32_e32 v23, v6
	v_mov_b32_e32 v24, v6
	v_mov_b32_e32 v25, v6
	v_mov_b32_e32 v26, v6
	v_mov_b32_e32 v27, v6
	v_mov_b32_e32 v28, v6
	v_mov_b32_e32 v29, v6
	v_mov_b32_e32 v38, v6
	v_mov_b32_e32 v39, v6
	v_mov_b32_e32 v40, v6
	v_mov_b32_e32 v41, v6
	v_mov_b32_e32 v42, v6
	v_mov_b32_e32 v43, v6
	v_mov_b32_e32 v44, v6
	v_mov_b32_e32 v45, v6
	v_mov_b32_e32 v54, v6
	v_mov_b32_e32 v55, v6
	v_mov_b32_e32 v56, v6
	v_mov_b32_e32 v57, v6
	v_mov_b32_e32 v58, v6
	v_mov_b32_e32 v59, v6
	v_mov_b32_e32 v60, v6
	v_mov_b32_e32 v61, v6
	v_mov_b32_e32 v2, v6
	v_mov_b32_e32 v3, v6
	v_mov_b32_e32 v4, v6
	v_mov_b32_e32 v5, v6
	v_mov_b32_e32 v10, v6
	v_mov_b32_e32 v11, v6
	v_mov_b32_e32 v12, v6
	v_mov_b32_e32 v13, v6
	v_mov_b32_e32 v18, v6
	v_mov_b32_e32 v19, v6
	v_mov_b32_e32 v20, v6
	v_mov_b32_e32 v21, v6
	v_mov_b32_e32 v30, v6
	v_mov_b32_e32 v31, v6
	v_mov_b32_e32 v32, v6
	v_mov_b32_e32 v33, v6
	v_mov_b32_e32 v34, v6
	v_mov_b32_e32 v35, v6
	v_mov_b32_e32 v36, v6
	v_mov_b32_e32 v37, v6
	v_mov_b32_e32 v46, v6
	v_mov_b32_e32 v47, v6
	v_mov_b32_e32 v48, v6
	v_mov_b32_e32 v49, v6
	v_mov_b32_e32 v50, v6
	v_mov_b32_e32 v51, v6
	v_mov_b32_e32 v52, v6
	v_mov_b32_e32 v53, v6
	v_mov_b32_e32 v62, v6
	v_mov_b32_e32 v63, v6
	v_mov_b32_e32 v64, v6
	v_mov_b32_e32 v65, v6
	v_mov_b32_e32 v70, v6
	v_mov_b32_e32 v71, v6
	v_mov_b32_e32 v72, v6
	v_mov_b32_e32 v73, v6
	v_mov_b32_e32 v74, v6
	v_mov_b32_e32 v75, v6
	v_mov_b32_e32 v76, v6
	v_mov_b32_e32 v77, v6
	v_mov_b32_e32 v86, v6
	v_mov_b32_e32 v87, v6
	v_mov_b32_e32 v88, v6
	v_mov_b32_e32 v89, v6
	v_mov_b32_e32 v90, v6
	v_mov_b32_e32 v91, v6
	v_mov_b32_e32 v92, v6
	v_mov_b32_e32 v93, v6
	v_mov_b32_e32 v102, v6
	v_mov_b32_e32 v103, v6
	v_mov_b32_e32 v104, v6
	v_mov_b32_e32 v105, v6
	v_mov_b32_e32 v106, v6
	v_mov_b32_e32 v107, v6
	v_mov_b32_e32 v108, v6
	v_mov_b32_e32 v109, v6
	v_mov_b32_e32 v118, v6
	v_mov_b32_e32 v119, v6
	v_mov_b32_e32 v120, v6
	v_mov_b32_e32 v121, v6
	v_mov_b32_e32 v126, v6
	v_mov_b32_e32 v127, v6
	v_mov_b32_e32 v128, v6
	v_mov_b32_e32 v129, v6
	v_mov_b32_e32 v66, v6
	v_mov_b32_e32 v67, v6
	v_mov_b32_e32 v68, v6
	v_mov_b32_e32 v69, v6
	v_mov_b32_e32 v78, v6
	v_mov_b32_e32 v79, v6
	v_mov_b32_e32 v80, v6
	v_mov_b32_e32 v81, v6
	v_mov_b32_e32 v82, v6
	v_mov_b32_e32 v83, v6
	v_mov_b32_e32 v84, v6
	v_mov_b32_e32 v85, v6
	v_mov_b32_e32 v94, v6
	v_mov_b32_e32 v95, v6
	v_mov_b32_e32 v96, v6
	v_mov_b32_e32 v97, v6
	v_mov_b32_e32 v98, v6
	v_mov_b32_e32 v99, v6
	v_mov_b32_e32 v100, v6
	v_mov_b32_e32 v101, v6
	v_mov_b32_e32 v110, v6
	v_mov_b32_e32 v111, v6
	v_mov_b32_e32 v112, v6
	v_mov_b32_e32 v113, v6
	v_mov_b32_e32 v114, v6
	v_mov_b32_e32 v115, v6
	v_mov_b32_e32 v116, v6
	v_mov_b32_e32 v117, v6
	v_mov_b32_e32 v122, v6
	v_mov_b32_e32 v123, v6
	v_mov_b32_e32 v124, v6
	v_mov_b32_e32 v125, v6

;     __device__ bool next(int i, Unit& u) const { const int L = i * G + c; if (L >= 512) return false; u.pm = 0; u.pn = L; u.offA = 0; u.offB = (size_t)L * 256 * 256 * 2; return true; }
; template <class Epi, class Sched>
; __device__ __forceinline__ void gemm_phase(LAS unsigned char* lds, const Gemm g, const Sched& S, const Epi& E) {
;     ...
;         const bool has_next = S.next(ui + 1, nxt);
;         const char* nA = has_next ? (const char*)g.A + nxt.offA : cA; const char* nB = has_next ? (const char*)g.Bt + nxt.offB : cB;
;         for (int t = 0; t < nt; t += 2) {
;             const bool last = (t == nt - 2);
;             const char* a1 = cA + (size_t)(t + 1) * kstep;
;             const char* a2 = last ? nA : cA + (size_t)(t + 2) * kstep; const char* b2 = last ? nB : cB + (size_t)(t + 2) * kstep;
;     ...
; #pragma unroll
;         for (int a = 0; a < 2; ++a)
; #pragma unroll
;             for (int b = 0; b < 2; ++b)
; #pragma unroll
;                 for (int m = 0; m < 4; ++m)
; #pragma unroll
;                     for (int n = 0; n < 2; ++n) acc[a][b][m][n] = (f32x4){0.f, 0.f, 0.f, 0.f};
;         cur = nxt; cA = nA; cB = nB; ++ui;
.LBB0_761:
	s_add_u32 s40, s54, s36
	s_addc_u32 s41, s55, s37
	s_andn2_b64 vcc, exec, s[8:9]
	s_cbranch_vccnz .Lzc_21902
	s_and_b64 s[44:45], s[38:39], exec
	s_cselect_b32 s52, s41, s43
	s_cselect_b32 s56, s40, s42
	s_add_u32 s57, s42, 0x100
	v_mov_b32_e32 v2, 0
	v_readlane_b32 s22, v250, 4
	s_addc_u32 s64, s43, 0
	s_mov_b32 s46, 0
	s_mov_b64 s[42:43], 0
	v_mov_b32_e32 v3, v2
	v_mov_b32_e32 v4, v2
	v_mov_b32_e32 v5, v2
	v_mov_b32_e32 v6, v2
	v_mov_b32_e32 v7, v2
	v_mov_b32_e32 v8, v2
	v_mov_b32_e32 v9, v2
	v_mov_b32_e32 v18, v2
	v_mov_b32_e32 v19, v2
	v_mov_b32_e32 v20, v2
	v_mov_b32_e32 v21, v2
	v_mov_b32_e32 v22, v2
	v_mov_b32_e32 v23, v2
	v_mov_b32_e32 v24, v2
	v_mov_b32_e32 v25, v2
	v_mov_b32_e32 v34, v2
	v_mov_b32_e32 v35, v2
	v_mov_b32_e32 v36, v2
	v_mov_b32_e32 v37, v2
	v_mov_b32_e32 v38, v2
	v_mov_b32_e32 v39, v2
	v_mov_b32_e32 v40, v2
	v_mov_b32_e32 v41, v2
	v_mov_b32_e32 v50, v2
	v_mov_b32_e32 v51, v2
	v_mov_b32_e32 v52, v2
	v_mov_b32_e32 v53, v2
	v_mov_b32_e32 v54, v2
	v_mov_b32_e32 v55, v2
	v_mov_b32_e32 v56, v2
	v_mov_b32_e32 v57, v2
	v_mov_b32_e32 v10, v2
	v_mov_b32_e32 v11, v2
	v_mov_b32_e32 v12, v2
	v_mov_b32_e32 v13, v2
	v_mov_b32_e32 v14, v2
	v_mov_b32_e32 v15, v2
	v_mov_b32_e32 v16, v2
	v_mov_b32_e32 v17, v2
	v_mov_b32_e32 v26, v2
	v_mov_b32_e32 v27, v2
	v_mov_b32_e32 v28, v2
	v_mov_b32_e32 v29, v2
	v_mov_b32_e32 v30, v2
	v_mov_b32_e32 v31, v2
	v_mov_b32_e32 v32, v2
	v_mov_b32_e32 v33, v2
	v_mov_b32_e32 v42, v2
	v_mov_b32_e32 v43, v2
	v_mov_b32_e32 v44, v2
	v_mov_b32_e32 v45, v2
	v_mov_b32_e32 v46, v2
	v_mov_b32_e32 v47, v2
	v_mov_b32_e32 v48, v2
	v_mov_b32_e32 v49, v2
	v_mov_b32_e32 v58, v2
	v_mov_b32_e32 v59, v2
	v_mov_b32_e32 v60, v2
	v_mov_b32_e32 v61, v2
	v_mov_b32_e32 v62, v2
	v_mov_b32_e32 v63, v2
	v_mov_b32_e32 v64, v2
	v_mov_b32_e32 v65, v2
	v_mov_b32_e32 v66, v2
	v_mov_b32_e32 v67, v2
	v_mov_b32_e32 v68, v2
	v_mov_b32_e32 v69, v2
	v_mov_b32_e32 v70, v2
	v_mov_b32_e32 v71, v2
	v_mov_b32_e32 v72, v2
	v_mov_b32_e32 v73, v2
	v_mov_b32_e32 v82, v2
	v_mov_b32_e32 v83, v2
	v_mov_b32_e32 v84, v2
	v_mov_b32_e32 v85, v2
	v_mov_b32_e32 v86, v2
	v_mov_b32_e32 v87, v2
	v_mov_b32_e32 v88, v2
	v_mov_b32_e32 v89, v2
	v_mov_b32_e32 v98, v2
	v_mov_b32_e32 v99, v2
	v_mov_b32_e32 v100, v2
	v_mov_b32_e32 v101, v2
	v_mov_b32_e32 v102, v2
	v_mov_b32_e32 v103, v2
	v_mov_b32_e32 v104, v2
	v_mov_b32_e32 v105, v2
	v_mov_b32_e32 v114, v2
	v_mov_b32_e32 v115, v2
	v_mov_b32_e32 v116, v2
	v_mov_b32_e32 v117, v2
	v_mov_b32_e32 v118, v2
	v_mov_b32_e32 v119, v2
	v_mov_b32_e32 v120, v2
	v_mov_b32_e32 v121, v2
	v_mov_b32_e32 v74, v2
	v_mov_b32_e32 v75, v2
	v_mov_b32_e32 v76, v2
	v_mov_b32_e32 v77, v2
	v_mov_b32_e32 v78, v2
	v_mov_b32_e32 v79, v2
	v_mov_b32_e32 v80, v2
	v_mov_b32_e32 v81, v2
	v_mov_b32_e32 v90, v2
	v_mov_b32_e32 v91, v2
	v_mov_b32_e32 v92, v2
	v_mov_b32_e32 v93, v2
	v_mov_b32_e32 v94, v2
	v_mov_b32_e32 v95, v2
	v_mov_b32_e32 v96, v2
	v_mov_b32_e32 v97, v2
	v_mov_b32_e32 v106, v2
	v_mov_b32_e32 v107, v2
	v_mov_b32_e32 v108, v2
	v_mov_b32_e32 v109, v2
	v_mov_b32_e32 v110, v2
	v_mov_b32_e32 v111, v2
	v_mov_b32_e32 v112, v2
	v_mov_b32_e32 v113, v2
	v_mov_b32_e32 v126, v2
	v_mov_b32_e32 v127, v2
	v_mov_b32_e32 v128, v2
	v_mov_b32_e32 v129, v2
	v_mov_b32_e32 v122, v2
	v_mov_b32_e32 v123, v2
	v_mov_b32_e32 v124, v2
	v_mov_b32_e32 v125, v2
	v_readlane_b32 s23, v250, 5
	v_readlane_b32 s78, v250, 36

;     __device__ bool next(int i, Unit& u) const { const int L = i * G + c; if (L >= 512) return false; u.pm = 0; u.pn = L; u.offA = 0; u.offB = (size_t)L * 256 * 256 * 2; return true; }
; template <class Epi, class Sched>
; __device__ __forceinline__ void gemm_phase(LAS unsigned char* lds, const Gemm g, const Sched& S, const Epi& E) {
;     ...
;         const bool has_next = S.next(ui + 1, nxt);
;         const char* nA = has_next ? (const char*)g.A + nxt.offA : cA; const char* nB = has_next ? (const char*)g.Bt + nxt.offB : cB;
;         for (int t = 0; t < nt; t += 2) {
;             const bool last = (t == nt - 2);
;             const char* a1 = cA + (size_t)(t + 1) * kstep;
;             const char* a2 = last ? nA : cA + (size_t)(t + 2) * kstep; const char* b2 = last ? nB : cB + (size_t)(t + 2) * kstep;
;     ...
; #pragma unroll
;         for (int a = 0; a < 2; ++a)
; #pragma unroll
;             for (int b = 0; b < 2; ++b)
; #pragma unroll
;                 for (int m = 0; m < 4; ++m)
; #pragma unroll
;                     for (int n = 0; n < 2; ++n) acc[a][b][m][n] = (f32x4){0.f, 0.f, 0.f, 0.f};
;         cur = nxt; cA = nA; cB = nB; ++ui;
.LBB0_834:
	v_readlane_b32 s0, v253, 38
	v_readlane_b32 s1, v253, 39
	s_add_u32 s46, s0, s42
	s_addc_u32 s47, s1, s43
	v_readlane_b32 s0, v253, 34
	v_readlane_b32 s1, v253, 35
	s_add_u32 s48, s0, s44
	s_addc_u32 s49, s1, s45
	s_andn2_b64 vcc, exec, s[8:9]
	s_cbranch_vccnz .Lzc_23745
	s_and_b64 s[0:1], s[38:39], exec
	s_cselect_b32 s10, s47, s51
	s_cselect_b32 s35, s46, s50
	s_cselect_b32 s41, s49, s77
	s_cselect_b32 s83, s48, s76
	s_lshl_b32 s36, s82, 8
	s_lshl_b32 s0, s80, 8
	s_add_i32 s36, s36, s30
	s_or_b32 s37, s0, s52
	s_add_u32 s50, s50, 0x40080
	s_addc_u32 s51, s51, 0
	v_mov_b32_e32 v2, v1
	v_mov_b32_e32 v3, v1
	s_add_u32 s0, s76, 0x100
	v_mov_b32_e32 v0, v1
	v_mov_b64_e32 v[6:7], v[2:3]
	v_mov_b64_e32 v[10:11], v[2:3]
	v_mov_b64_e32 v[22:23], v[2:3]
	v_mov_b64_e32 v[26:27], v[2:3]
	v_mov_b64_e32 v[38:39], v[2:3]
	v_mov_b64_e32 v[42:43], v[2:3]
	v_mov_b64_e32 v[54:55], v[2:3]
	v_mov_b64_e32 v[58:59], v[2:3]
	v_mov_b64_e32 v[14:15], v[2:3]
	v_mov_b64_e32 v[18:19], v[2:3]
	v_mov_b64_e32 v[30:31], v[2:3]
	v_mov_b64_e32 v[34:35], v[2:3]
	v_mov_b64_e32 v[46:47], v[2:3]
	v_mov_b64_e32 v[50:51], v[2:3]
	v_mov_b64_e32 v[62:63], v[2:3]
	v_mov_b64_e32 v[66:67], v[2:3]
	v_mov_b64_e32 v[70:71], v[2:3]
	v_mov_b64_e32 v[74:75], v[2:3]
	v_mov_b64_e32 v[86:87], v[2:3]
	v_mov_b64_e32 v[90:91], v[2:3]
	v_mov_b64_e32 v[102:103], v[2:3]
	v_mov_b64_e32 v[106:107], v[2:3]
	v_mov_b64_e32 v[122:123], v[2:3]
	v_mov_b64_e32 v[118:119], v[2:3]
	v_mov_b64_e32 v[78:79], v[2:3]
	v_mov_b64_e32 v[82:83], v[2:3]
	v_mov_b64_e32 v[94:95], v[2:3]
	v_mov_b64_e32 v[98:99], v[2:3]
	v_mov_b64_e32 v[110:111], v[2:3]
	v_mov_b64_e32 v[114:115], v[2:3]
	v_mov_b64_e32 v[130:131], v[2:3]
	v_mov_b64_e32 v[126:127], v[2:3]
	s_addc_u32 s1, s77, 0
	s_mov_b32 s76, 0
	v_mov_b64_e32 v[4:5], v[0:1]
	v_mov_b64_e32 v[8:9], v[0:1]
	v_mov_b64_e32 v[20:21], v[0:1]
	v_mov_b64_e32 v[24:25], v[0:1]
	v_mov_b64_e32 v[36:37], v[0:1]
	v_mov_b64_e32 v[40:41], v[0:1]
	v_mov_b64_e32 v[52:53], v[0:1]
	v_mov_b64_e32 v[56:57], v[0:1]
	v_mov_b64_e32 v[12:13], v[0:1]
	v_mov_b64_e32 v[16:17], v[0:1]
	v_mov_b64_e32 v[28:29], v[0:1]
	v_mov_b64_e32 v[32:33], v[0:1]
	v_mov_b64_e32 v[44:45], v[0:1]
	v_mov_b64_e32 v[48:49], v[0:1]
	v_mov_b64_e32 v[60:61], v[0:1]
	v_mov_b64_e32 v[64:65], v[0:1]
	v_mov_b64_e32 v[68:69], v[0:1]
	v_mov_b64_e32 v[72:73], v[0:1]
	v_mov_b64_e32 v[84:85], v[0:1]
	v_mov_b64_e32 v[88:89], v[0:1]
	v_mov_b64_e32 v[100:101], v[0:1]
	v_mov_b64_e32 v[104:105], v[0:1]
	v_mov_b64_e32 v[120:121], v[0:1]
	v_mov_b64_e32 v[116:117], v[0:1]
	v_mov_b64_e32 v[76:77], v[0:1]
	v_mov_b64_e32 v[80:81], v[0:1]
	v_mov_b64_e32 v[92:93], v[0:1]
	v_mov_b64_e32 v[96:97], v[0:1]
	v_mov_b64_e32 v[108:109], v[0:1]
	v_mov_b64_e32 v[112:113], v[0:1]
	v_mov_b64_e32 v[128:129], v[0:1]
	v_mov_b64_e32 v[124:125], v[0:1]
	s_cmp_lg_u32 s73, s76
	s_cbranch_scc1 .LBB0_837

; template <class Epi, class Sched>
; __device__ __forceinline__ void gemm_phase(LAS unsigned char* lds, const Gemm g, const Sched& S, const Epi& E) {
;     ...
; #pragma unroll
;         for (int a = 0; a < 2; ++a)
; #pragma unroll
;             for (int b = 0; b < 2; ++b)
; #pragma unroll
;                 for (int m = 0; m < 4; ++m)
; #pragma unroll
;                     for (int n = 0; n < 2; ++n) acc[a][b][m][n] = (f32x4){0.f, 0.f, 0.f, 0.f};
.Lzc_23745:
	v_mov_b32_e32 v127, 0
	v_mov_b32_e32 v126, v127
	v_mov_b32_e32 v125, v127
	v_mov_b32_e32 v124, v127
	v_mov_b32_e32 v131, v127
	v_mov_b32_e32 v130, v127
	v_mov_b32_e32 v129, v127
	v_mov_b32_e32 v128, v127
	v_mov_b32_e32 v115, v127
	v_mov_b32_e32 v114, v127
	v_mov_b32_e32 v113, v127
	v_mov_b32_e32 v112, v127
	v_mov_b32_e32 v111, v127
	v_mov_b32_e32 v110, v127
	v_mov_b32_e32 v109, v127
	v_mov_b32_e32 v108, v127
	v_mov_b32_e32 v99, v127
	v_mov_b32_e32 v98, v127
	v_mov_b32_e32 v97, v127
	v_mov_b32_e32 v96, v127
	v_mov_b32_e32 v95, v127
	v_mov_b32_e32 v94, v127
	v_mov_b32_e32 v93, v127
	v_mov_b32_e32 v92, v127
	v_mov_b32_e32 v83, v127
	v_mov_b32_e32 v82, v127
	v_mov_b32_e32 v81, v127
	v_mov_b32_e32 v80, v127
	v_mov_b32_e32 v79, v127
	v_mov_b32_e32 v78, v127
	v_mov_b32_e32 v77, v127
	v_mov_b32_e32 v76, v127
	v_mov_b32_e32 v119, v127
	v_mov_b32_e32 v118, v127
	v_mov_b32_e32 v117, v127
	v_mov_b32_e32 v116, v127
	v_mov_b32_e32 v123, v127
	v_mov_b32_e32 v122, v127
	v_mov_b32_e32 v121, v127
	v_mov_b32_e32 v120, v127
	v_mov_b32_e32 v107, v127
	v_mov_b32_e32 v106, v127
	v_mov_b32_e32 v105, v127
	v_mov_b32_e32 v104, v127
	v_mov_b32_e32 v103, v127
	v_mov_b32_e32 v102, v127
	v_mov_b32_e32 v101, v127
	v_mov_b32_e32 v100, v127
	v_mov_b32_e32 v91, v127
	v_mov_b32_e32 v90, v127
	v_mov_b32_e32 v89, v127
	v_mov_b32_e32 v88, v127
	v_mov_b32_e32 v87, v127
	v_mov_b32_e32 v86, v127
	v_mov_b32_e32 v85, v127
	v_mov_b32_e32 v84, v127
	v_mov_b32_e32 v75, v127
	v_mov_b32_e32 v74, v127
	v_mov_b32_e32 v73, v127
	v_mov_b32_e32 v72, v127
	v_mov_b32_e32 v71, v127
	v_mov_b32_e32 v70, v127
	v_mov_b32_e32 v69, v127
	v_mov_b32_e32 v68, v127
	v_mov_b32_e32 v67, v127
	v_mov_b32_e32 v66, v127
	v_mov_b32_e32 v65, v127
	v_mov_b32_e32 v64, v127
	v_mov_b32_e32 v63, v127
	v_mov_b32_e32 v62, v127
	v_mov_b32_e32 v61, v127
	v_mov_b32_e32 v60, v127
	v_mov_b32_e32 v51, v127
	v_mov_b32_e32 v50, v127
	v_mov_b32_e32 v49, v127
	v_mov_b32_e32 v48, v127
	v_mov_b32_e32 v47, v127
	v_mov_b32_e32 v46, v127
	v_mov_b32_e32 v45, v127
	v_mov_b32_e32 v44, v127
	v_mov_b32_e32 v35, v127
	v_mov_b32_e32 v34, v127
	v_mov_b32_e32 v33, v127
	v_mov_b32_e32 v32, v127
	v_mov_b32_e32 v31, v127
	v_mov_b32_e32 v30, v127
	v_mov_b32_e32 v29, v127
	v_mov_b32_e32 v28, v127
	v_mov_b32_e32 v19, v127
	v_mov_b32_e32 v18, v127
	v_mov_b32_e32 v17, v127
	v_mov_b32_e32 v16, v127
	v_mov_b32_e32 v15, v127
	v_mov_b32_e32 v14, v127
	v_mov_b32_e32 v13, v127
	v_mov_b32_e32 v12, v127
	v_mov_b32_e32 v59, v127
	v_mov_b32_e32 v58, v127
	v_mov_b32_e32 v57, v127
	v_mov_b32_e32 v56, v127
	v_mov_b32_e32 v55, v127
	v_mov_b32_e32 v54, v127
	v_mov_b32_e32 v53, v127
	v_mov_b32_e32 v52, v127
	v_mov_b32_e32 v43, v127
	v_mov_b32_e32 v42, v127
	v_mov_b32_e32 v41, v127
	v_mov_b32_e32 v40, v127
	v_mov_b32_e32 v39, v127
	v_mov_b32_e32 v38, v127
	v_mov_b32_e32 v37, v127
	v_mov_b32_e32 v36, v127
	v_mov_b32_e32 v27, v127
	v_mov_b32_e32 v26, v127
	v_mov_b32_e32 v25, v127
	v_mov_b32_e32 v24, v127
	v_mov_b32_e32 v23, v127
	v_mov_b32_e32 v22, v127
	v_mov_b32_e32 v21, v127
	v_mov_b32_e32 v20, v127
	v_mov_b32_e32 v11, v127
	v_mov_b32_e32 v10, v127
	v_mov_b32_e32 v9, v127
	v_mov_b32_e32 v8, v127
	v_mov_b32_e32 v7, v127
	v_mov_b32_e32 v6, v127
	v_mov_b32_e32 v5, v127
	v_mov_b32_e32 v4, v127
	s_branch .LBB0_840

;     __device__ bool next(int i, Unit& u) const { const int L = i * G + c; if (L >= 512) return false; u.pm = 0; u.pn = L; u.offA = 0; u.offB = (size_t)L * 256 * 256 * 2; return true; }
; template <class Epi, class Sched>
; __device__ __forceinline__ void gemm_phase(LAS unsigned char* lds, const Gemm g, const Sched& S, const Epi& E) {
;     ...
;         const bool has_next = S.next(ui + 1, nxt);
;         const char* nA = has_next ? (const char*)g.A + nxt.offA : cA; const char* nB = has_next ? (const char*)g.Bt + nxt.offB : cB;
;         for (int t = 0; t < nt; t += 2) {
;             const bool last = (t == nt - 2);
;             const char* a1 = cA + (size_t)(t + 1) * kstep;
;             const char* a2 = last ? nA : cA + (size_t)(t + 2) * kstep; const char* b2 = last ? nB : cB + (size_t)(t + 2) * kstep;
;     ...
; #pragma unroll
;         for (int a = 0; a < 2; ++a)
; #pragma unroll
;             for (int b = 0; b < 2; ++b)
; #pragma unroll
;                 for (int m = 0; m < 4; ++m)
; #pragma unroll
;                     for (int n = 0; n < 2; ++n) acc[a][b][m][n] = (f32x4){0.f, 0.f, 0.f, 0.f};
;         cur = nxt; cA = nA; cB = nB; ++ui;
.LBB0_910:
	s_add_u32 s46, s54, s42
	s_addc_u32 s47, s55, s43
	v_readlane_b32 s22, v254, 12
	v_readlane_b32 s23, v254, 13
	s_add_u32 s48, s22, s44
	s_addc_u32 s49, s23, s45
	s_andn2_b64 vcc, exec, s[20:21]
	s_waitcnt lgkmcnt(0)
	s_cbranch_vccnz .Lzc_25928
	s_and_b64 s[76:77], s[36:37], exec
	s_cselect_b32 s39, s47, s1
	s_cselect_b32 s41, s46, s0
	s_cselect_b32 s82, s49, s51
	s_cselect_b32 s83, s48, s50
	s_add_u32 s0, s0, 0x40080
	s_addc_u32 s1, s1, 0
	s_add_u32 s84, s50, 0x100
	v_mov_b32_e32 v2, 0
	s_addc_u32 s85, s51, 0
	s_mov_b32 s50, 0
	v_mov_b32_e32 v3, v2
	v_mov_b32_e32 v4, v2
	v_mov_b32_e32 v5, v2
	v_mov_b32_e32 v6, v2
	v_mov_b32_e32 v7, v2
	v_mov_b32_e32 v8, v2
	v_mov_b32_e32 v9, v2
	v_mov_b32_e32 v18, v2
	v_mov_b32_e32 v19, v2
	v_mov_b32_e32 v20, v2
	v_mov_b32_e32 v21, v2
	v_mov_b32_e32 v22, v2
	v_mov_b32_e32 v23, v2
	v_mov_b32_e32 v24, v2
	v_mov_b32_e32 v25, v2
	v_mov_b32_e32 v34, v2
	v_mov_b32_e32 v35, v2
	v_mov_b32_e32 v36, v2
	v_mov_b32_e32 v37, v2
	v_mov_b32_e32 v38, v2
	v_mov_b32_e32 v39, v2
	v_mov_b32_e32 v40, v2
	v_mov_b32_e32 v41, v2
	v_mov_b32_e32 v50, v2
	v_mov_b32_e32 v51, v2
	v_mov_b32_e32 v52, v2
	v_mov_b32_e32 v53, v2
	v_mov_b32_e32 v54, v2
	v_mov_b32_e32 v55, v2
	v_mov_b32_e32 v56, v2
	v_mov_b32_e32 v57, v2
	v_mov_b32_e32 v10, v2
	v_mov_b32_e32 v11, v2
	v_mov_b32_e32 v12, v2
	v_mov_b32_e32 v13, v2
	v_mov_b32_e32 v14, v2
	v_mov_b32_e32 v15, v2
	v_mov_b32_e32 v16, v2
	v_mov_b32_e32 v17, v2
	v_mov_b32_e32 v26, v2
	v_mov_b32_e32 v27, v2
	v_mov_b32_e32 v28, v2
	v_mov_b32_e32 v29, v2
	v_mov_b32_e32 v30, v2
	v_mov_b32_e32 v31, v2
	v_mov_b32_e32 v32, v2
	v_mov_b32_e32 v33, v2
	v_mov_b32_e32 v42, v2
	v_mov_b32_e32 v43, v2
	v_mov_b32_e32 v44, v2
	v_mov_b32_e32 v45, v2
	v_mov_b32_e32 v46, v2
	v_mov_b32_e32 v47, v2
	v_mov_b32_e32 v48, v2
	v_mov_b32_e32 v49, v2
	v_mov_b32_e32 v58, v2
	v_mov_b32_e32 v59, v2
	v_mov_b32_e32 v60, v2
	v_mov_b32_e32 v61, v2
	v_mov_b32_e32 v62, v2
	v_mov_b32_e32 v63, v2
	v_mov_b32_e32 v64, v2
	v_mov_b32_e32 v65, v2
	v_mov_b32_e32 v66, v2
	v_mov_b32_e32 v67, v2
	v_mov_b32_e32 v68, v2
	v_mov_b32_e32 v69, v2
	v_mov_b32_e32 v70, v2
	v_mov_b32_e32 v71, v2
	v_mov_b32_e32 v72, v2
	v_mov_b32_e32 v73, v2
	v_mov_b32_e32 v82, v2
	v_mov_b32_e32 v83, v2
	v_mov_b32_e32 v84, v2
	v_mov_b32_e32 v85, v2
	v_mov_b32_e32 v86, v2
	v_mov_b32_e32 v87, v2
	v_mov_b32_e32 v88, v2
	v_mov_b32_e32 v89, v2
	v_mov_b32_e32 v98, v2
	v_mov_b32_e32 v99, v2
	v_mov_b32_e32 v100, v2
	v_mov_b32_e32 v101, v2
	v_mov_b32_e32 v102, v2
	v_mov_b32_e32 v103, v2
	v_mov_b32_e32 v104, v2
	v_mov_b32_e32 v105, v2
	v_mov_b32_e32 v114, v2
	v_mov_b32_e32 v115, v2
	v_mov_b32_e32 v116, v2
	v_mov_b32_e32 v117, v2
	v_mov_b32_e32 v118, v2
	v_mov_b32_e32 v119, v2
	v_mov_b32_e32 v120, v2
	v_mov_b32_e32 v121, v2
	v_mov_b32_e32 v74, v2
	v_mov_b32_e32 v75, v2
	v_mov_b32_e32 v76, v2
	v_mov_b32_e32 v77, v2
	v_mov_b32_e32 v78, v2
	v_mov_b32_e32 v79, v2
	v_mov_b32_e32 v80, v2
	v_mov_b32_e32 v81, v2
	v_mov_b32_e32 v90, v2
	v_mov_b32_e32 v91, v2
	v_mov_b32_e32 v92, v2
	v_mov_b32_e32 v93, v2
	v_mov_b32_e32 v94, v2
	v_mov_b32_e32 v95, v2
	v_mov_b32_e32 v96, v2
	v_mov_b32_e32 v97, v2
	v_mov_b32_e32 v106, v2
	v_mov_b32_e32 v107, v2
	v_mov_b32_e32 v108, v2
	v_mov_b32_e32 v109, v2
	v_mov_b32_e32 v110, v2
	v_mov_b32_e32 v111, v2
	v_mov_b32_e32 v112, v2
	v_mov_b32_e32 v113, v2
	v_mov_b32_e32 v126, v2
	v_mov_b32_e32 v127, v2
	v_mov_b32_e32 v128, v2
	v_mov_b32_e32 v129, v2
	v_mov_b32_e32 v122, v2
	v_mov_b32_e32 v123, v2
	v_mov_b32_e32 v124, v2
	v_mov_b32_e32 v125, v2
